# v53 + ds_bpermute xor16/xor32 exchanges in P2 sgu / P3 / P4' / P6' / P8 epilogues replaced by v_mov + v_permlane16/32_swap (bitwise-identical sums)
# baseline (speedup 1.0000x reference)
.LBB0_390:
	v_lshl_add_u64 v[12:13], v[10:11], 0, s[42:43]
	s_mov_b32 s8, 0x100000
	s_mov_b32 s9, 0
	global_load_dwordx4 v[176:179], v[12:13], off
	v_lshl_add_u64 v[12:13], v[12:13], 0, s[8:9]
	global_load_dwordx4 v[180:183], v[12:13], off
	v_lshl_add_u64 v[12:13], v[12:13], 0, s[8:9]
	global_load_dwordx4 v[184:187], v[12:13], off
	v_lshl_add_u64 v[12:13], v[12:13], 0, s[8:9]
	global_load_dwordx4 v[188:191], v[12:13], off
	v_lshl_add_u64 v[12:13], v[12:13], 0, s[8:9]
	global_load_dwordx4 v[192:195], v[12:13], off
	v_lshl_add_u64 v[12:13], v[12:13], 0, s[8:9]
	global_load_dwordx4 v[196:199], v[12:13], off
	v_lshl_add_u64 v[12:13], v[12:13], 0, s[8:9]
	global_load_dwordx4 v[200:203], v[12:13], off
	v_lshl_add_u64 v[12:13], v[12:13], 0, s[8:9]
	global_load_dwordx4 v[204:207], v[12:13], off
	v_lshl_add_u64 v[12:13], v[12:13], 0, s[8:9]
	global_load_dwordx4 v[208:211], v[12:13], off
	v_lshl_add_u64 v[12:13], v[12:13], 0, s[8:9]
	global_load_dwordx4 v[212:215], v[12:13], off
	v_lshl_add_u64 v[12:13], v[12:13], 0, s[8:9]
	global_load_dwordx4 v[216:219], v[12:13], off
	v_lshl_add_u64 v[12:13], v[12:13], 0, s[8:9]
	global_load_dwordx4 v[220:223], v[12:13], off
	v_lshl_add_u64 v[12:13], v[12:13], 0, s[8:9]
	global_load_dwordx4 v[224:227], v[12:13], off
	v_lshl_add_u64 v[12:13], v[12:13], 0, s[8:9]
	global_load_dwordx4 v[228:231], v[12:13], off
	v_lshl_add_u64 v[12:13], v[12:13], 0, s[8:9]
	global_load_dwordx4 v[232:235], v[12:13], off
	v_lshl_add_u64 v[12:13], v[12:13], 0, s[8:9]
	global_load_dwordx4 v[236:239], v[12:13], off
	v_lshl_add_u64 v[12:13], v[12:13], 0, s[8:9]
	s_mov_b32 s8, 0x1000000
	v_lshl_add_u64 v[10:11], v[10:11], 0, s[8:9]
	s_add_u32 s46, s46, 1
	s_waitcnt vmcnt(15)
	v_lshlrev_b32_e32 v20, 16, v176
	v_and_b32_e32 v21, 0xffff0000, v176
	v_lshlrev_b32_e32 v22, 16, v177
	v_and_b32_e32 v23, 0xffff0000, v177
	v_lshlrev_b32_e32 v24, 16, v178
	v_and_b32_e32 v25, 0xffff0000, v178
	v_lshlrev_b32_e32 v26, 16, v179
	v_and_b32_e32 v27, 0xffff0000, v179
	v_pk_fma_f32 v[8:9], v[20:21], v[20:21], v[8:9]
	v_pk_fma_f32 v[6:7], v[22:23], v[22:23], v[6:7]
	v_pk_fma_f32 v[4:5], v[24:25], v[24:25], v[4:5]
	v_pk_fma_f32 v[2:3], v[26:27], v[26:27], v[2:3]
	s_waitcnt vmcnt(14)
	v_lshlrev_b32_e32 v20, 16, v180
	v_and_b32_e32 v21, 0xffff0000, v180
	v_lshlrev_b32_e32 v22, 16, v181
	v_and_b32_e32 v23, 0xffff0000, v181
	v_lshlrev_b32_e32 v24, 16, v182
	v_and_b32_e32 v25, 0xffff0000, v182
	v_lshlrev_b32_e32 v26, 16, v183
	v_and_b32_e32 v27, 0xffff0000, v183
	v_pk_fma_f32 v[8:9], v[20:21], v[20:21], v[8:9]
	v_pk_fma_f32 v[6:7], v[22:23], v[22:23], v[6:7]
	v_pk_fma_f32 v[4:5], v[24:25], v[24:25], v[4:5]
	v_pk_fma_f32 v[2:3], v[26:27], v[26:27], v[2:3]
	s_waitcnt vmcnt(13)
	v_lshlrev_b32_e32 v20, 16, v184
	v_and_b32_e32 v21, 0xffff0000, v184
	v_lshlrev_b32_e32 v22, 16, v185
	v_and_b32_e32 v23, 0xffff0000, v185
	v_lshlrev_b32_e32 v24, 16, v186
	v_and_b32_e32 v25, 0xffff0000, v186
	v_lshlrev_b32_e32 v26, 16, v187
	v_and_b32_e32 v27, 0xffff0000, v187
	v_pk_fma_f32 v[8:9], v[20:21], v[20:21], v[8:9]
	v_pk_fma_f32 v[6:7], v[22:23], v[22:23], v[6:7]
	v_pk_fma_f32 v[4:5], v[24:25], v[24:25], v[4:5]
	v_pk_fma_f32 v[2:3], v[26:27], v[26:27], v[2:3]
	s_waitcnt vmcnt(12)
	v_lshlrev_b32_e32 v20, 16, v188
	v_and_b32_e32 v21, 0xffff0000, v188
	v_lshlrev_b32_e32 v22, 16, v189
	v_and_b32_e32 v23, 0xffff0000, v189
	v_lshlrev_b32_e32 v24, 16, v190
	v_and_b32_e32 v25, 0xffff0000, v190
	v_lshlrev_b32_e32 v26, 16, v191
	v_and_b32_e32 v27, 0xffff0000, v191
	v_pk_fma_f32 v[8:9], v[20:21], v[20:21], v[8:9]
	v_pk_fma_f32 v[6:7], v[22:23], v[22:23], v[6:7]
	v_pk_fma_f32 v[4:5], v[24:25], v[24:25], v[4:5]
	v_pk_fma_f32 v[2:3], v[26:27], v[26:27], v[2:3]
	s_waitcnt vmcnt(11)
	v_lshlrev_b32_e32 v20, 16, v192
	v_and_b32_e32 v21, 0xffff0000, v192
	v_lshlrev_b32_e32 v22, 16, v193
	v_and_b32_e32 v23, 0xffff0000, v193
	v_lshlrev_b32_e32 v24, 16, v194
	v_and_b32_e32 v25, 0xffff0000, v194
	v_lshlrev_b32_e32 v26, 16, v195
	v_and_b32_e32 v27, 0xffff0000, v195
	v_pk_fma_f32 v[8:9], v[20:21], v[20:21], v[8:9]
	v_pk_fma_f32 v[6:7], v[22:23], v[22:23], v[6:7]
	v_pk_fma_f32 v[4:5], v[24:25], v[24:25], v[4:5]
	v_pk_fma_f32 v[2:3], v[26:27], v[26:27], v[2:3]
	s_waitcnt vmcnt(10)
	v_lshlrev_b32_e32 v20, 16, v196
	v_and_b32_e32 v21, 0xffff0000, v196
	v_lshlrev_b32_e32 v22, 16, v197
	v_and_b32_e32 v23, 0xffff0000, v197
	v_lshlrev_b32_e32 v24, 16, v198
	v_and_b32_e32 v25, 0xffff0000, v198
	v_lshlrev_b32_e32 v26, 16, v199
	v_and_b32_e32 v27, 0xffff0000, v199
	v_pk_fma_f32 v[8:9], v[20:21], v[20:21], v[8:9]
	v_pk_fma_f32 v[6:7], v[22:23], v[22:23], v[6:7]
	v_pk_fma_f32 v[4:5], v[24:25], v[24:25], v[4:5]
	v_pk_fma_f32 v[2:3], v[26:27], v[26:27], v[2:3]
	s_waitcnt vmcnt(9)
	v_lshlrev_b32_e32 v20, 16, v200
	v_and_b32_e32 v21, 0xffff0000, v200
	v_lshlrev_b32_e32 v22, 16, v201
	v_and_b32_e32 v23, 0xffff0000, v201
	v_lshlrev_b32_e32 v24, 16, v202
	v_and_b32_e32 v25, 0xffff0000, v202
	v_lshlrev_b32_e32 v26, 16, v203
	v_and_b32_e32 v27, 0xffff0000, v203
	v_pk_fma_f32 v[8:9], v[20:21], v[20:21], v[8:9]
	v_pk_fma_f32 v[6:7], v[22:23], v[22:23], v[6:7]
	v_pk_fma_f32 v[4:5], v[24:25], v[24:25], v[4:5]
	v_pk_fma_f32 v[2:3], v[26:27], v[26:27], v[2:3]
	s_waitcnt vmcnt(8)
	v_lshlrev_b32_e32 v20, 16, v204
	v_and_b32_e32 v21, 0xffff0000, v204
	v_lshlrev_b32_e32 v22, 16, v205
	v_and_b32_e32 v23, 0xffff0000, v205
	v_lshlrev_b32_e32 v24, 16, v206
	v_and_b32_e32 v25, 0xffff0000, v206
	v_lshlrev_b32_e32 v26, 16, v207
	v_and_b32_e32 v27, 0xffff0000, v207
	v_pk_fma_f32 v[8:9], v[20:21], v[20:21], v[8:9]
	v_pk_fma_f32 v[6:7], v[22:23], v[22:23], v[6:7]
	v_pk_fma_f32 v[4:5], v[24:25], v[24:25], v[4:5]
	v_pk_fma_f32 v[2:3], v[26:27], v[26:27], v[2:3]
	s_waitcnt vmcnt(7)
	v_lshlrev_b32_e32 v20, 16, v208
	v_and_b32_e32 v21, 0xffff0000, v208
	v_lshlrev_b32_e32 v22, 16, v209
	v_and_b32_e32 v23, 0xffff0000, v209
	v_lshlrev_b32_e32 v24, 16, v210
	v_and_b32_e32 v25, 0xffff0000, v210
	v_lshlrev_b32_e32 v26, 16, v211
	v_and_b32_e32 v27, 0xffff0000, v211
	v_pk_fma_f32 v[8:9], v[20:21], v[20:21], v[8:9]
	v_pk_fma_f32 v[6:7], v[22:23], v[22:23], v[6:7]
	v_pk_fma_f32 v[4:5], v[24:25], v[24:25], v[4:5]
	v_pk_fma_f32 v[2:3], v[26:27], v[26:27], v[2:3]
	s_waitcnt vmcnt(6)
	v_lshlrev_b32_e32 v20, 16, v212
	v_and_b32_e32 v21, 0xffff0000, v212
	v_lshlrev_b32_e32 v22, 16, v213
	v_and_b32_e32 v23, 0xffff0000, v213
	v_lshlrev_b32_e32 v24, 16, v214
	v_and_b32_e32 v25, 0xffff0000, v214
	v_lshlrev_b32_e32 v26, 16, v215
	v_and_b32_e32 v27, 0xffff0000, v215
	v_pk_fma_f32 v[8:9], v[20:21], v[20:21], v[8:9]
	v_pk_fma_f32 v[6:7], v[22:23], v[22:23], v[6:7]
	v_pk_fma_f32 v[4:5], v[24:25], v[24:25], v[4:5]
	v_pk_fma_f32 v[2:3], v[26:27], v[26:27], v[2:3]
	s_waitcnt vmcnt(5)
	v_lshlrev_b32_e32 v20, 16, v216
	v_and_b32_e32 v21, 0xffff0000, v216
	v_lshlrev_b32_e32 v22, 16, v217
	v_and_b32_e32 v23, 0xffff0000, v217
	v_lshlrev_b32_e32 v24, 16, v218
	v_and_b32_e32 v25, 0xffff0000, v218
	v_lshlrev_b32_e32 v26, 16, v219
	v_and_b32_e32 v27, 0xffff0000, v219
	v_pk_fma_f32 v[8:9], v[20:21], v[20:21], v[8:9]
	v_pk_fma_f32 v[6:7], v[22:23], v[22:23], v[6:7]
	v_pk_fma_f32 v[4:5], v[24:25], v[24:25], v[4:5]
	v_pk_fma_f32 v[2:3], v[26:27], v[26:27], v[2:3]
	s_waitcnt vmcnt(4)
	v_lshlrev_b32_e32 v20, 16, v220
	v_and_b32_e32 v21, 0xffff0000, v220
	v_lshlrev_b32_e32 v22, 16, v221
	v_and_b32_e32 v23, 0xffff0000, v221
	v_lshlrev_b32_e32 v24, 16, v222
	v_and_b32_e32 v25, 0xffff0000, v222
	v_lshlrev_b32_e32 v26, 16, v223
	v_and_b32_e32 v27, 0xffff0000, v223
	v_pk_fma_f32 v[8:9], v[20:21], v[20:21], v[8:9]
	v_pk_fma_f32 v[6:7], v[22:23], v[22:23], v[6:7]
	v_pk_fma_f32 v[4:5], v[24:25], v[24:25], v[4:5]
	v_pk_fma_f32 v[2:3], v[26:27], v[26:27], v[2:3]
	s_waitcnt vmcnt(3)
	v_lshlrev_b32_e32 v20, 16, v224
	v_and_b32_e32 v21, 0xffff0000, v224
	v_lshlrev_b32_e32 v22, 16, v225
	v_and_b32_e32 v23, 0xffff0000, v225
	v_lshlrev_b32_e32 v24, 16, v226
	v_and_b32_e32 v25, 0xffff0000, v226
	v_lshlrev_b32_e32 v26, 16, v227
	v_and_b32_e32 v27, 0xffff0000, v227
	v_pk_fma_f32 v[8:9], v[20:21], v[20:21], v[8:9]
	v_pk_fma_f32 v[6:7], v[22:23], v[22:23], v[6:7]
	v_pk_fma_f32 v[4:5], v[24:25], v[24:25], v[4:5]
	v_pk_fma_f32 v[2:3], v[26:27], v[26:27], v[2:3]
	s_waitcnt vmcnt(2)
	v_lshlrev_b32_e32 v20, 16, v228
	v_and_b32_e32 v21, 0xffff0000, v228
	v_lshlrev_b32_e32 v22, 16, v229
	v_and_b32_e32 v23, 0xffff0000, v229
	v_lshlrev_b32_e32 v24, 16, v230
	v_and_b32_e32 v25, 0xffff0000, v230
	v_lshlrev_b32_e32 v26, 16, v231
	v_and_b32_e32 v27, 0xffff0000, v231
	v_pk_fma_f32 v[8:9], v[20:21], v[20:21], v[8:9]
	v_pk_fma_f32 v[6:7], v[22:23], v[22:23], v[6:7]
	v_pk_fma_f32 v[4:5], v[24:25], v[24:25], v[4:5]
	v_pk_fma_f32 v[2:3], v[26:27], v[26:27], v[2:3]
	s_waitcnt vmcnt(1)
	v_lshlrev_b32_e32 v20, 16, v232
	v_and_b32_e32 v21, 0xffff0000, v232
	v_lshlrev_b32_e32 v22, 16, v233
	v_and_b32_e32 v23, 0xffff0000, v233
	v_lshlrev_b32_e32 v24, 16, v234
	v_and_b32_e32 v25, 0xffff0000, v234
	v_lshlrev_b32_e32 v26, 16, v235
	v_and_b32_e32 v27, 0xffff0000, v235
	v_pk_fma_f32 v[8:9], v[20:21], v[20:21], v[8:9]
	v_pk_fma_f32 v[6:7], v[22:23], v[22:23], v[6:7]
	v_pk_fma_f32 v[4:5], v[24:25], v[24:25], v[4:5]
	v_pk_fma_f32 v[2:3], v[26:27], v[26:27], v[2:3]
	s_waitcnt vmcnt(0)
	v_lshlrev_b32_e32 v20, 16, v236
	v_and_b32_e32 v21, 0xffff0000, v236
	v_lshlrev_b32_e32 v22, 16, v237
	v_and_b32_e32 v23, 0xffff0000, v237
	v_lshlrev_b32_e32 v24, 16, v238
	v_and_b32_e32 v25, 0xffff0000, v238
	v_lshlrev_b32_e32 v26, 16, v239
	v_and_b32_e32 v27, 0xffff0000, v239
	v_pk_fma_f32 v[8:9], v[20:21], v[20:21], v[8:9]
	v_pk_fma_f32 v[6:7], v[22:23], v[22:23], v[6:7]
	v_pk_fma_f32 v[4:5], v[24:25], v[24:25], v[4:5]
	v_pk_fma_f32 v[2:3], v[26:27], v[26:27], v[2:3]
	s_cmp_eq_u32 s46, 2
	s_cbranch_scc0 .LBB0_390
	v_and_b32_e32 v10, 64, v114
	v_xor_b32_e32 v1, 16, v114
	v_add_u32_e32 v12, 64, v10
	v_cmp_lt_i32_e32 vcc, v1, v12
	v_xor_b32_e32 v13, 32, v114
	s_nop 0
	v_cndmask_b32_e32 v1, v114, v1, vcc
	v_cmp_lt_i32_e32 vcc, v13, v12
	v_lshlrev_b32_e32 v1, 2, v1
	v_mov_b32_e32 v10, v8
	s_nop 1
	v_permlane16_swap_b32_e32 v8, v10
	v_cndmask_b32_e32 v14, v114, v13, vcc
	v_mov_b32_e32 v11, v9
	s_nop 1
	v_permlane16_swap_b32_e32 v9, v11
	v_mov_b32_e32 v12, v6
	s_nop 1
	v_permlane16_swap_b32_e32 v6, v12
	v_mov_b32_e32 v13, v7
	s_nop 1
	v_permlane16_swap_b32_e32 v7, v13
	v_lshlrev_b32_e32 v19, 2, v14
	v_mov_b32_e32 v14, v4
	s_nop 1
	v_permlane16_swap_b32_e32 v4, v14
	v_mov_b32_e32 v15, v5
	s_nop 1
	v_permlane16_swap_b32_e32 v5, v15
	v_mov_b32_e32 v16, v2
	s_nop 1
	v_permlane16_swap_b32_e32 v2, v16
	v_mov_b32_e32 v17, v3
	s_nop 1
	v_permlane16_swap_b32_e32 v3, v17
	s_waitcnt lgkmcnt(6)
	v_pk_add_f32 v[8:9], v[8:9], v[10:11]
	s_waitcnt lgkmcnt(4)
	v_pk_add_f32 v[6:7], v[6:7], v[12:13]
	s_waitcnt lgkmcnt(2)
	v_pk_add_f32 v[4:5], v[4:5], v[14:15]
	v_mov_b32_e32 v10, v8
	s_nop 1
	v_permlane32_swap_b32_e32 v8, v10
	s_waitcnt lgkmcnt(1)
	v_pk_add_f32 v[2:3], v[2:3], v[16:17]
	v_mov_b32_e32 v11, v9
	s_nop 1
	v_permlane32_swap_b32_e32 v9, v11
	v_mov_b32_e32 v12, v6
	s_nop 1
	v_permlane32_swap_b32_e32 v6, v12
	v_mov_b32_e32 v13, v7
	s_nop 1
	v_permlane32_swap_b32_e32 v7, v13
	v_mov_b32_e32 v14, v4
	s_nop 1
	v_permlane32_swap_b32_e32 v4, v14
	v_mov_b32_e32 v15, v5
	s_nop 1
	v_permlane32_swap_b32_e32 v5, v15
	v_mov_b32_e32 v16, v2
	s_nop 1
	v_permlane32_swap_b32_e32 v2, v16
	v_mov_b32_e32 v17, v3
	s_nop 1
	v_permlane32_swap_b32_e32 v3, v17
	v_bfe_u32 v19, v18, 4, 2
	v_and_b32_e32 v1, 15, v18
	v_cmp_eq_u32_e32 vcc, 0, v19
	s_and_saveexec_b64 s[8:9], vcc
	s_cbranch_execz .LBB0_393
	v_lshlrev_b32_e32 v20, 3, v18
	v_and_b32_e32 v20, 0xfffffe00, v20
	v_lshlrev_b32_e32 v21, 5, v1
	v_add3_u32 v20, 0, v20, v21
	s_waitcnt lgkmcnt(6)
	v_pk_add_f32 v[8:9], v[8:9], v[10:11]
	s_waitcnt lgkmcnt(4)
	v_pk_add_f32 v[10:11], v[6:7], v[12:13]
	s_waitcnt lgkmcnt(2)
	v_pk_add_f32 v[4:5], v[4:5], v[14:15]
	s_waitcnt lgkmcnt(0)
	v_pk_add_f32 v[6:7], v[2:3], v[16:17]
	ds_write_b128 v20, v[8:11]
	ds_write_b128 v20, v[4:7] offset:16

.LBB0_505:
	v_lshl_or_b32 v168, s26, 8, v178
	s_lshl_b32 s43, s50, 8
	v_ashrrev_i32_e32 v169, 31, v168
	v_add_u32_e32 v170, s43, v176
	v_lshlrev_b64 v[206:207], 1, v[168:169]
	v_ashrrev_i32_e32 v171, 31, v170
	v_lshl_add_u64 v[172:173], s[28:29], 0, v[206:207]
	v_lshlrev_b64 v[208:209], 12, v[170:171]
	v_lshl_add_u64 v[128:129], v[172:173], 0, v[208:209]
	global_load_dwordx4 v[198:201], v[128:129], off
	global_load_dwordx4 v[202:205], v[128:129], off offset:256
	v_or_b32_e32 v128, 16, v170
	v_or_b32_e32 v130, 32, v170
	v_or_b32_e32 v132, 48, v170
	v_ashrrev_i32_e32 v129, 31, v128
	v_ashrrev_i32_e32 v131, 31, v130
	v_ashrrev_i32_e32 v133, 31, v132
	v_lshlrev_b64 v[128:129], 12, v[128:129]
	v_lshlrev_b64 v[130:131], 12, v[130:131]
	v_lshlrev_b64 v[132:133], 12, v[132:133]
	v_lshl_add_u64 v[128:129], v[172:173], 0, v[128:129]
	v_lshl_add_u64 v[130:131], v[172:173], 0, v[130:131]
	v_lshl_add_u64 v[196:197], v[172:173], 0, v[132:133]
	global_load_dwordx4 v[148:151], v[128:129], off
	global_load_dwordx4 v[144:147], v[128:129], off offset:256
	global_load_dwordx4 v[140:143], v[130:131], off
	global_load_dwordx4 v[136:139], v[130:131], off offset:256
	global_load_dwordx4 v[132:135], v[196:197], off
	s_nop 0
	global_load_dwordx4 v[128:131], v[196:197], off offset:256
	v_and_b32_e32 v196, 64, v195
	v_xor_b32_e32 v171, 16, v195
	v_add_u32_e32 v196, 64, v196
	v_xor_b32_e32 v197, 32, v195
	v_cmp_lt_i32_e32 vcc, v171, v196
	s_waitcnt vmcnt(0)
	v_lshlrev_b32_e32 v210, 16, v198
	v_cndmask_b32_e32 v171, v195, v171, vcc
	v_cmp_lt_i32_e32 vcc, v197, v196
	v_and_b32_e32 v211, 0xffff0000, v198
	v_lshlrev_b32_e32 v198, 16, v199
	v_and_b32_e32 v199, 0xffff0000, v199
	v_lshlrev_b32_e32 v212, 16, v200
	v_and_b32_e32 v213, 0xffff0000, v200
	v_lshlrev_b32_e32 v200, 16, v201
	v_and_b32_e32 v201, 0xffff0000, v201
	v_lshlrev_b32_e32 v214, 16, v202
	v_and_b32_e32 v215, 0xffff0000, v202
	v_lshlrev_b32_e32 v202, 16, v203
	v_and_b32_e32 v203, 0xffff0000, v203
	v_lshlrev_b32_e32 v216, 16, v204
	v_and_b32_e32 v217, 0xffff0000, v204
	v_lshlrev_b32_e32 v204, 16, v205
	v_and_b32_e32 v205, 0xffff0000, v205
	v_cndmask_b32_e32 v197, v195, v197, vcc
	v_pk_add_f32 v[126:127], v[126:127], v[198:199]
	v_pk_add_f32 v[124:125], v[124:125], v[210:211]
	v_pk_add_f32 v[122:123], v[122:123], v[200:201]
	v_pk_add_f32 v[120:121], v[120:121], v[212:213]
	v_pk_add_f32 v[118:119], v[118:119], v[202:203]
	v_pk_add_f32 v[116:117], v[116:117], v[214:215]
	v_pk_add_f32 v[198:199], v[114:115], v[204:205]
	v_pk_add_f32 v[200:201], v[112:113], v[216:217]
	v_lshlrev_b32_e32 v196, 2, v171
	v_lshlrev_b32_e32 v171, 2, v197
	v_cvt_pk_bf16_f32 v112, v124, v125
	v_cvt_pk_bf16_f32 v113, v126, v127
	v_cvt_pk_bf16_f32 v114, v120, v121
	v_cvt_pk_bf16_f32 v115, v122, v123
	v_mul_f32_e32 v125, v125, v125
	v_mul_f32_e32 v127, v127, v127
	v_mul_f32_e32 v121, v121, v121
	v_mul_f32_e32 v123, v123, v123
	v_mul_f32_e32 v197, v117, v117
	v_mul_f32_e32 v202, v119, v119
	v_mul_f32_e32 v203, v201, v201
	v_mul_f32_e32 v204, v199, v199
	v_fmac_f32_e32 v125, v124, v124
	v_fmac_f32_e32 v127, v126, v126
	v_fmac_f32_e32 v121, v120, v120
	v_fmac_f32_e32 v123, v122, v122
	v_fmac_f32_e32 v197, v116, v116
	v_fmac_f32_e32 v202, v118, v118
	v_fmac_f32_e32 v203, v200, v200
	v_fmac_f32_e32 v204, v198, v198
	v_add_f32_e32 v120, v125, v127
	v_add_f32_e32 v121, v121, v123
	v_add_f32_e32 v122, v197, v202
	v_add_f32_e32 v123, v203, v204
	v_add_f32_e32 v120, v120, v121
	v_add_f32_e32 v121, v122, v123
	v_add_f32_e32 v122, v120, v121
	v_mov_b32_e32 v123, v122
	s_nop 1
	v_permlane16_swap_b32_e32 v122, v123
	v_lshl_add_u64 v[120:121], s[28:29], 0, v[208:209]
	v_lshl_add_u64 v[120:121], v[120:121], 0, v[206:207]
	global_store_dwordx4 v[120:121], v[112:115], off
	s_waitcnt lgkmcnt(0)
	s_nop 0
	v_add_f32_e32 v112, v122, v123
	v_mov_b32_e32 v113, v112
	s_nop 1
	v_permlane32_swap_b32_e32 v112, v113
	v_cvt_pk_bf16_f32 v114, v116, v117
	v_cvt_pk_bf16_f32 v115, v118, v119
	v_cvt_pk_bf16_f32 v116, v200, v201
	v_cvt_pk_bf16_f32 v117, v198, v199
	global_store_dwordx4 v[120:121], v[114:117], off offset:256
	s_and_saveexec_b64 s[50:51], s[6:7]
	s_cbranch_execz .LBB0_507
	s_waitcnt lgkmcnt(0)
	v_add_f32_e32 v112, v112, v113
	ds_write_b32 v187, v112
.LBB0_507:
	s_or_b64 exec, exec, s[50:51]
	v_lshlrev_b32_e32 v114, 16, v148
	v_and_b32_e32 v115, 0xffff0000, v148
	v_lshlrev_b32_e32 v116, 16, v149
	v_and_b32_e32 v117, 0xffff0000, v149
	v_lshlrev_b32_e32 v118, 16, v150
	v_and_b32_e32 v119, 0xffff0000, v150
	v_pk_add_f32 v[108:109], v[108:109], v[114:115]
	v_pk_add_f32 v[110:111], v[110:111], v[116:117]
	v_pk_add_f32 v[116:117], v[104:105], v[118:119]
	v_cvt_pk_bf16_f32 v104, v108, v109
	v_mul_f32_e32 v109, v109, v109
	v_lshlrev_b32_e32 v120, 16, v151
	v_and_b32_e32 v121, 0xffff0000, v151
	v_fmac_f32_e32 v109, v108, v108
	v_mul_f32_e32 v108, v111, v111
	v_pk_add_f32 v[114:115], v[106:107], v[120:121]
	v_fmac_f32_e32 v108, v110, v110
	v_cvt_pk_bf16_f32 v105, v110, v111
	v_add_f32_e32 v108, v109, v108
	v_mul_f32_e32 v109, v117, v117
	v_mul_f32_e32 v110, v115, v115
	v_fmac_f32_e32 v109, v116, v116
	v_fmac_f32_e32 v110, v114, v114
	v_add_f32_e32 v109, v109, v110
	v_add_f32_e32 v118, v108, v109
	v_lshlrev_b32_e32 v108, 16, v144
	v_and_b32_e32 v109, 0xffff0000, v144
	v_lshlrev_b32_e32 v110, 16, v145
	v_and_b32_e32 v111, 0xffff0000, v145
	v_cvt_pk_bf16_f32 v107, v114, v115
	v_lshlrev_b32_e32 v114, 16, v146
	v_and_b32_e32 v115, 0xffff0000, v146
	v_pk_add_f32 v[102:103], v[102:103], v[110:111]
	v_pk_add_f32 v[100:101], v[100:101], v[108:109]
	v_cvt_pk_bf16_f32 v106, v116, v117
	v_lshlrev_b32_e32 v116, 16, v147
	v_and_b32_e32 v117, 0xffff0000, v147
	v_pk_add_f32 v[110:111], v[96:97], v[114:115]
	v_mul_f32_e32 v96, v101, v101
	v_mul_f32_e32 v97, v103, v103
	v_pk_add_f32 v[108:109], v[98:99], v[116:117]
	v_fmac_f32_e32 v96, v100, v100
	v_fmac_f32_e32 v97, v102, v102
	v_add_f32_e32 v96, v96, v97
	v_mul_f32_e32 v97, v111, v111
	v_mul_f32_e32 v98, v109, v109
	v_fmac_f32_e32 v97, v110, v110
	v_fmac_f32_e32 v98, v108, v108
	v_add_f32_e32 v97, v97, v98
	v_add_f32_e32 v96, v96, v97
	v_add_f32_e32 v99, v118, v96
	v_mov_b32_e32 v114, v99
	s_nop 1
	v_permlane16_swap_b32_e32 v99, v114
	v_add_u32_e32 v112, s43, v179
	s_waitcnt lgkmcnt(1)
	v_ashrrev_i32_e32 v113, 31, v112
	v_lshlrev_b64 v[112:113], 12, v[112:113]
	v_lshl_add_u64 v[96:97], s[28:29], 0, v[112:113]
	v_lshl_add_u64 v[112:113], v[168:169], 1, v[96:97]
	s_waitcnt lgkmcnt(0)
	v_add_f32_e32 v96, v99, v114
	v_mov_b32_e32 v97, v96
	s_nop 1
	v_permlane32_swap_b32_e32 v96, v97
	v_cvt_pk_bf16_f32 v98, v100, v101
	v_cvt_pk_bf16_f32 v99, v102, v103
	v_cvt_pk_bf16_f32 v100, v110, v111
	v_cvt_pk_bf16_f32 v101, v108, v109
	global_store_dwordx4 v[112:113], v[104:107], off
	global_store_dwordx4 v[112:113], v[98:101], off offset:256
	s_and_saveexec_b64 s[50:51], s[6:7]
	s_cbranch_execz .LBB0_509
	s_waitcnt lgkmcnt(0)
	v_add_f32_e32 v96, v96, v97
	ds_write_b32 v188, v96
.LBB0_509:
	s_or_b64 exec, exec, s[50:51]
	v_lshlrev_b32_e32 v98, 16, v140
	v_and_b32_e32 v99, 0xffff0000, v140
	v_lshlrev_b32_e32 v100, 16, v141
	v_and_b32_e32 v101, 0xffff0000, v141
	v_lshlrev_b32_e32 v102, 16, v142
	v_and_b32_e32 v103, 0xffff0000, v142
	v_pk_add_f32 v[92:93], v[92:93], v[98:99]
	v_pk_add_f32 v[94:95], v[94:95], v[100:101]
	v_pk_add_f32 v[100:101], v[88:89], v[102:103]
	v_cvt_pk_bf16_f32 v88, v92, v93
	v_mul_f32_e32 v93, v93, v93
	v_lshlrev_b32_e32 v104, 16, v143
	v_and_b32_e32 v105, 0xffff0000, v143
	v_fmac_f32_e32 v93, v92, v92
	v_mul_f32_e32 v92, v95, v95
	v_pk_add_f32 v[98:99], v[90:91], v[104:105]
	v_fmac_f32_e32 v92, v94, v94
	v_cvt_pk_bf16_f32 v89, v94, v95
	v_add_f32_e32 v92, v93, v92
	v_mul_f32_e32 v93, v101, v101
	v_mul_f32_e32 v94, v99, v99
	v_fmac_f32_e32 v93, v100, v100
	v_fmac_f32_e32 v94, v98, v98
	v_add_f32_e32 v93, v93, v94
	v_add_f32_e32 v102, v92, v93
	v_lshlrev_b32_e32 v92, 16, v136
	v_and_b32_e32 v93, 0xffff0000, v136
	v_lshlrev_b32_e32 v94, 16, v137
	v_and_b32_e32 v95, 0xffff0000, v137
	v_cvt_pk_bf16_f32 v91, v98, v99
	v_lshlrev_b32_e32 v98, 16, v138
	v_and_b32_e32 v99, 0xffff0000, v138
	v_pk_add_f32 v[86:87], v[86:87], v[94:95]
	v_pk_add_f32 v[84:85], v[84:85], v[92:93]
	v_cvt_pk_bf16_f32 v90, v100, v101
	v_lshlrev_b32_e32 v100, 16, v139
	v_and_b32_e32 v101, 0xffff0000, v139
	v_pk_add_f32 v[94:95], v[80:81], v[98:99]
	v_mul_f32_e32 v80, v85, v85
	v_mul_f32_e32 v81, v87, v87
	v_pk_add_f32 v[92:93], v[82:83], v[100:101]
	v_fmac_f32_e32 v80, v84, v84
	v_fmac_f32_e32 v81, v86, v86
	v_add_f32_e32 v80, v80, v81
	v_mul_f32_e32 v81, v95, v95
	v_mul_f32_e32 v82, v93, v93
	v_fmac_f32_e32 v81, v94, v94
	v_fmac_f32_e32 v82, v92, v92
	v_add_f32_e32 v81, v81, v82
	v_add_f32_e32 v80, v80, v81
	v_add_f32_e32 v83, v102, v80
	v_mov_b32_e32 v98, v83
	s_nop 1
	v_permlane16_swap_b32_e32 v83, v98
	v_add_u32_e32 v96, s43, v180
	s_waitcnt lgkmcnt(1)
	v_ashrrev_i32_e32 v97, 31, v96
	v_lshlrev_b64 v[96:97], 12, v[96:97]
	v_lshl_add_u64 v[80:81], s[28:29], 0, v[96:97]
	v_lshl_add_u64 v[96:97], v[168:169], 1, v[80:81]
	s_waitcnt lgkmcnt(0)
	v_add_f32_e32 v80, v83, v98
	v_mov_b32_e32 v81, v80
	s_nop 1
	v_permlane32_swap_b32_e32 v80, v81
	v_cvt_pk_bf16_f32 v82, v84, v85
	v_cvt_pk_bf16_f32 v83, v86, v87
	v_cvt_pk_bf16_f32 v84, v94, v95
	v_cvt_pk_bf16_f32 v85, v92, v93
	global_store_dwordx4 v[96:97], v[88:91], off
	global_store_dwordx4 v[96:97], v[82:85], off offset:256
	s_and_saveexec_b64 s[50:51], s[6:7]
	s_cbranch_execz .LBB0_511
	s_waitcnt lgkmcnt(0)
	v_add_f32_e32 v80, v80, v81
	ds_write_b32 v189, v80
.LBB0_511:
	s_or_b64 exec, exec, s[50:51]
	v_lshlrev_b32_e32 v82, 16, v132
	v_and_b32_e32 v83, 0xffff0000, v132
	v_lshlrev_b32_e32 v84, 16, v133
	v_and_b32_e32 v85, 0xffff0000, v133
	v_lshlrev_b32_e32 v86, 16, v134
	v_and_b32_e32 v87, 0xffff0000, v134
	v_pk_add_f32 v[76:77], v[76:77], v[82:83]
	v_pk_add_f32 v[78:79], v[78:79], v[84:85]
	v_pk_add_f32 v[84:85], v[72:73], v[86:87]
	v_cvt_pk_bf16_f32 v72, v76, v77
	v_mul_f32_e32 v77, v77, v77
	v_lshlrev_b32_e32 v88, 16, v135
	v_and_b32_e32 v89, 0xffff0000, v135
	v_fmac_f32_e32 v77, v76, v76
	v_mul_f32_e32 v76, v79, v79
	v_pk_add_f32 v[82:83], v[74:75], v[88:89]
	v_fmac_f32_e32 v76, v78, v78
	v_cvt_pk_bf16_f32 v73, v78, v79
	v_add_f32_e32 v76, v77, v76
	v_mul_f32_e32 v77, v85, v85
	v_mul_f32_e32 v78, v83, v83
	v_fmac_f32_e32 v77, v84, v84
	v_fmac_f32_e32 v78, v82, v82
	v_add_f32_e32 v77, v77, v78
	v_add_f32_e32 v86, v76, v77
	v_lshlrev_b32_e32 v76, 16, v128
	v_and_b32_e32 v77, 0xffff0000, v128
	v_lshlrev_b32_e32 v78, 16, v129
	v_and_b32_e32 v79, 0xffff0000, v129
	v_cvt_pk_bf16_f32 v75, v82, v83
	v_lshlrev_b32_e32 v82, 16, v130
	v_and_b32_e32 v83, 0xffff0000, v130
	v_pk_add_f32 v[70:71], v[70:71], v[78:79]
	v_pk_add_f32 v[68:69], v[68:69], v[76:77]
	v_cvt_pk_bf16_f32 v74, v84, v85
	v_lshlrev_b32_e32 v84, 16, v131
	v_and_b32_e32 v85, 0xffff0000, v131
	v_pk_add_f32 v[78:79], v[64:65], v[82:83]
	v_mul_f32_e32 v64, v69, v69
	v_mul_f32_e32 v65, v71, v71
	v_pk_add_f32 v[76:77], v[66:67], v[84:85]
	v_fmac_f32_e32 v64, v68, v68
	v_fmac_f32_e32 v65, v70, v70
	v_add_f32_e32 v64, v64, v65
	v_mul_f32_e32 v65, v79, v79
	v_mul_f32_e32 v66, v77, v77
	v_fmac_f32_e32 v65, v78, v78
	v_fmac_f32_e32 v66, v76, v76
	v_add_f32_e32 v65, v65, v66
	v_add_f32_e32 v64, v64, v65
	v_add_f32_e32 v67, v86, v64
	v_mov_b32_e32 v82, v67
	s_nop 1
	v_permlane16_swap_b32_e32 v67, v82
	v_add_u32_e32 v80, s43, v181
	s_waitcnt lgkmcnt(1)
	v_ashrrev_i32_e32 v81, 31, v80
	v_lshlrev_b64 v[80:81], 12, v[80:81]
	v_lshl_add_u64 v[64:65], s[28:29], 0, v[80:81]
	v_lshl_add_u64 v[80:81], v[168:169], 1, v[64:65]
	s_waitcnt lgkmcnt(0)
	v_add_f32_e32 v64, v67, v82
	v_mov_b32_e32 v65, v64
	s_nop 1
	v_permlane32_swap_b32_e32 v64, v65
	v_cvt_pk_bf16_f32 v66, v68, v69
	v_cvt_pk_bf16_f32 v67, v70, v71
	v_cvt_pk_bf16_f32 v68, v78, v79
	v_cvt_pk_bf16_f32 v69, v76, v77
	global_store_dwordx4 v[80:81], v[72:75], off
	global_store_dwordx4 v[80:81], v[66:69], off offset:256
	s_and_saveexec_b64 s[50:51], s[6:7]
	s_cbranch_execz .LBB0_513
	s_waitcnt lgkmcnt(0)
	v_add_f32_e32 v64, v64, v65
	ds_write_b32 v190, v64
.LBB0_513:
	s_or_b64 exec, exec, s[50:51]
	v_add_u32_e32 v64, s43, v182
	s_waitcnt lgkmcnt(0)
	v_ashrrev_i32_e32 v65, 31, v64
	v_lshlrev_b64 v[96:97], 12, v[64:65]
	v_lshl_add_u64 v[66:67], v[172:173], 0, v[96:97]
	global_load_dwordx4 v[88:91], v[66:67], off
	global_load_dwordx4 v[92:95], v[66:67], off offset:256
	v_or_b32_e32 v66, 16, v64
	v_or_b32_e32 v68, 32, v64
	v_or_b32_e32 v64, 48, v64
	v_ashrrev_i32_e32 v67, 31, v66
	v_ashrrev_i32_e32 v69, 31, v68
	v_ashrrev_i32_e32 v65, 31, v64
	v_lshlrev_b64 v[66:67], 12, v[66:67]
	v_lshlrev_b64 v[68:69], 12, v[68:69]
	v_lshlrev_b64 v[64:65], 12, v[64:65]
	v_lshl_add_u64 v[66:67], v[172:173], 0, v[66:67]
	v_lshl_add_u64 v[68:69], v[172:173], 0, v[68:69]
	v_lshl_add_u64 v[64:65], v[172:173], 0, v[64:65]
	global_load_dwordx4 v[84:87], v[66:67], off
	global_load_dwordx4 v[80:83], v[66:67], off offset:256
	global_load_dwordx4 v[76:79], v[68:69], off
	global_load_dwordx4 v[72:75], v[68:69], off offset:256
	s_nop 0
	global_load_dwordx4 v[68:71], v[64:65], off
	s_nop 0
	global_load_dwordx4 v[64:67], v[64:65], off offset:256
	s_waitcnt vmcnt(7)
	v_lshlrev_b32_e32 v98, 16, v88
	v_and_b32_e32 v99, 0xffff0000, v88
	v_lshlrev_b32_e32 v88, 16, v89
	v_and_b32_e32 v89, 0xffff0000, v89
	v_lshlrev_b32_e32 v100, 16, v90
	v_and_b32_e32 v101, 0xffff0000, v90
	v_lshlrev_b32_e32 v90, 16, v91
	v_and_b32_e32 v91, 0xffff0000, v91
	s_waitcnt vmcnt(6)
	v_lshlrev_b32_e32 v102, 16, v92
	v_and_b32_e32 v103, 0xffff0000, v92
	v_lshlrev_b32_e32 v92, 16, v93
	v_and_b32_e32 v93, 0xffff0000, v93
	v_lshlrev_b32_e32 v104, 16, v94
	v_and_b32_e32 v105, 0xffff0000, v94
	v_lshlrev_b32_e32 v94, 16, v95
	v_and_b32_e32 v95, 0xffff0000, v95
	v_pk_add_f32 v[62:63], v[62:63], v[88:89]
	v_pk_add_f32 v[60:61], v[60:61], v[98:99]
	v_pk_add_f32 v[58:59], v[58:59], v[90:91]
	v_pk_add_f32 v[56:57], v[56:57], v[100:101]
	v_pk_add_f32 v[54:55], v[54:55], v[92:93]
	v_pk_add_f32 v[52:53], v[52:53], v[102:103]
	v_pk_add_f32 v[88:89], v[50:51], v[94:95]
	v_pk_add_f32 v[90:91], v[48:49], v[104:105]
	v_cvt_pk_bf16_f32 v48, v60, v61
	v_cvt_pk_bf16_f32 v49, v62, v63
	v_cvt_pk_bf16_f32 v50, v56, v57
	v_cvt_pk_bf16_f32 v51, v58, v59
	v_mul_f32_e32 v61, v61, v61
	v_mul_f32_e32 v63, v63, v63
	v_mul_f32_e32 v57, v57, v57
	v_mul_f32_e32 v59, v59, v59
	v_mul_f32_e32 v92, v53, v53
	v_mul_f32_e32 v93, v55, v55
	v_mul_f32_e32 v94, v91, v91
	v_mul_f32_e32 v95, v89, v89
	v_fmac_f32_e32 v61, v60, v60
	v_fmac_f32_e32 v63, v62, v62
	v_fmac_f32_e32 v57, v56, v56
	v_fmac_f32_e32 v59, v58, v58
	v_fmac_f32_e32 v92, v52, v52
	v_fmac_f32_e32 v93, v54, v54
	v_fmac_f32_e32 v94, v90, v90
	v_fmac_f32_e32 v95, v88, v88
	v_add_f32_e32 v56, v61, v63
	v_add_f32_e32 v57, v57, v59
	v_add_f32_e32 v58, v92, v93
	v_add_f32_e32 v59, v94, v95
	v_add_f32_e32 v56, v56, v57
	v_add_f32_e32 v57, v58, v59
	v_add_f32_e32 v58, v56, v57
	v_mov_b32_e32 v59, v58
	s_nop 1
	v_permlane16_swap_b32_e32 v58, v59
	v_lshl_add_u64 v[56:57], s[28:29], 0, v[96:97]
	v_lshl_add_u64 v[56:57], v[168:169], 1, v[56:57]
	global_store_dwordx4 v[56:57], v[48:51], off
	s_waitcnt lgkmcnt(0)
	s_nop 0
	v_add_f32_e32 v48, v58, v59
	v_mov_b32_e32 v49, v48
	s_nop 1
	v_permlane32_swap_b32_e32 v48, v49
	v_cvt_pk_bf16_f32 v50, v52, v53
	v_cvt_pk_bf16_f32 v51, v54, v55
	v_cvt_pk_bf16_f32 v52, v90, v91
	v_cvt_pk_bf16_f32 v53, v88, v89
	global_store_dwordx4 v[56:57], v[50:53], off offset:256
	s_and_saveexec_b64 s[50:51], s[6:7]
	s_cbranch_execz .LBB0_515
	s_waitcnt lgkmcnt(0)
	v_add_f32_e32 v48, v48, v49
	ds_write_b32 v191, v48
.LBB0_515:
	s_or_b64 exec, exec, s[50:51]
	s_waitcnt vmcnt(7)
	v_lshlrev_b32_e32 v50, 16, v84
	v_and_b32_e32 v51, 0xffff0000, v84
	v_lshlrev_b32_e32 v52, 16, v85
	v_and_b32_e32 v53, 0xffff0000, v85
	v_lshlrev_b32_e32 v54, 16, v86
	v_and_b32_e32 v55, 0xffff0000, v86
	v_pk_add_f32 v[44:45], v[44:45], v[50:51]
	v_pk_add_f32 v[46:47], v[46:47], v[52:53]
	v_pk_add_f32 v[52:53], v[40:41], v[54:55]
	v_cvt_pk_bf16_f32 v40, v44, v45
	v_mul_f32_e32 v45, v45, v45
	v_lshlrev_b32_e32 v56, 16, v87
	v_and_b32_e32 v57, 0xffff0000, v87
	v_fmac_f32_e32 v45, v44, v44
	v_mul_f32_e32 v44, v47, v47
	v_pk_add_f32 v[50:51], v[42:43], v[56:57]
	v_fmac_f32_e32 v44, v46, v46
	v_cvt_pk_bf16_f32 v41, v46, v47
	v_add_f32_e32 v44, v45, v44
	v_mul_f32_e32 v45, v53, v53
	v_mul_f32_e32 v46, v51, v51
	v_fmac_f32_e32 v45, v52, v52
	v_fmac_f32_e32 v46, v50, v50
	v_add_f32_e32 v45, v45, v46
	v_add_f32_e32 v54, v44, v45
	s_waitcnt vmcnt(6)
	v_lshlrev_b32_e32 v44, 16, v80
	v_and_b32_e32 v45, 0xffff0000, v80
	v_lshlrev_b32_e32 v46, 16, v81
	v_and_b32_e32 v47, 0xffff0000, v81
	v_cvt_pk_bf16_f32 v43, v50, v51
	v_lshlrev_b32_e32 v50, 16, v82
	v_and_b32_e32 v51, 0xffff0000, v82
	v_pk_add_f32 v[38:39], v[38:39], v[46:47]
	v_pk_add_f32 v[36:37], v[36:37], v[44:45]
	v_cvt_pk_bf16_f32 v42, v52, v53
	v_lshlrev_b32_e32 v52, 16, v83
	v_and_b32_e32 v53, 0xffff0000, v83
	v_pk_add_f32 v[46:47], v[32:33], v[50:51]
	v_mul_f32_e32 v32, v37, v37
	v_mul_f32_e32 v33, v39, v39
	v_pk_add_f32 v[44:45], v[34:35], v[52:53]
	v_fmac_f32_e32 v32, v36, v36
	v_fmac_f32_e32 v33, v38, v38
	v_add_f32_e32 v32, v32, v33
	v_mul_f32_e32 v33, v47, v47
	v_mul_f32_e32 v34, v45, v45
	v_fmac_f32_e32 v33, v46, v46
	v_fmac_f32_e32 v34, v44, v44
	v_add_f32_e32 v33, v33, v34
	v_add_f32_e32 v32, v32, v33
	v_add_f32_e32 v35, v54, v32
	v_mov_b32_e32 v50, v35
	s_nop 1
	v_permlane16_swap_b32_e32 v35, v50
	v_add_u32_e32 v48, 0x90, v170
	s_waitcnt lgkmcnt(1)
	v_ashrrev_i32_e32 v49, 31, v48
	v_lshlrev_b64 v[48:49], 12, v[48:49]
	v_lshl_add_u64 v[32:33], s[28:29], 0, v[48:49]
	v_lshl_add_u64 v[48:49], v[168:169], 1, v[32:33]
	s_waitcnt lgkmcnt(0)
	v_add_f32_e32 v32, v35, v50
	v_mov_b32_e32 v33, v32
	s_nop 1
	v_permlane32_swap_b32_e32 v32, v33
	v_cvt_pk_bf16_f32 v34, v36, v37
	v_cvt_pk_bf16_f32 v35, v38, v39
	v_cvt_pk_bf16_f32 v36, v46, v47
	v_cvt_pk_bf16_f32 v37, v44, v45
	global_store_dwordx4 v[48:49], v[40:43], off
	global_store_dwordx4 v[48:49], v[34:37], off offset:256
	s_and_saveexec_b64 s[50:51], s[6:7]
	s_cbranch_execz .LBB0_517
	s_waitcnt lgkmcnt(0)
	v_add_f32_e32 v32, v32, v33
	ds_write_b32 v187, v32 offset:2304
.LBB0_517:
	s_or_b64 exec, exec, s[50:51]
	s_waitcnt vmcnt(7)
	v_lshlrev_b32_e32 v34, 16, v76
	v_and_b32_e32 v35, 0xffff0000, v76
	v_lshlrev_b32_e32 v36, 16, v77
	v_and_b32_e32 v37, 0xffff0000, v77
	v_lshlrev_b32_e32 v38, 16, v78
	v_and_b32_e32 v39, 0xffff0000, v78
	v_pk_add_f32 v[28:29], v[28:29], v[34:35]
	v_pk_add_f32 v[30:31], v[30:31], v[36:37]
	v_pk_add_f32 v[36:37], v[24:25], v[38:39]
	v_cvt_pk_bf16_f32 v24, v28, v29
	v_mul_f32_e32 v29, v29, v29
	v_lshlrev_b32_e32 v40, 16, v79
	v_and_b32_e32 v41, 0xffff0000, v79
	v_fmac_f32_e32 v29, v28, v28
	v_mul_f32_e32 v28, v31, v31
	v_pk_add_f32 v[34:35], v[26:27], v[40:41]
	v_fmac_f32_e32 v28, v30, v30
	v_cvt_pk_bf16_f32 v25, v30, v31
	v_add_f32_e32 v28, v29, v28
	v_mul_f32_e32 v29, v37, v37
	v_mul_f32_e32 v30, v35, v35
	v_fmac_f32_e32 v29, v36, v36
	v_fmac_f32_e32 v30, v34, v34
	v_add_f32_e32 v29, v29, v30
	v_add_f32_e32 v38, v28, v29
	s_waitcnt vmcnt(6)
	v_lshlrev_b32_e32 v28, 16, v72
	v_and_b32_e32 v29, 0xffff0000, v72
	v_lshlrev_b32_e32 v30, 16, v73
	v_and_b32_e32 v31, 0xffff0000, v73
	v_cvt_pk_bf16_f32 v27, v34, v35
	v_lshlrev_b32_e32 v34, 16, v74
	v_and_b32_e32 v35, 0xffff0000, v74
	v_pk_add_f32 v[22:23], v[22:23], v[30:31]
	v_pk_add_f32 v[20:21], v[20:21], v[28:29]
	v_cvt_pk_bf16_f32 v26, v36, v37
	v_lshlrev_b32_e32 v36, 16, v75
	v_and_b32_e32 v37, 0xffff0000, v75
	v_pk_add_f32 v[30:31], v[16:17], v[34:35]
	v_mul_f32_e32 v16, v21, v21
	v_mul_f32_e32 v17, v23, v23
	v_pk_add_f32 v[28:29], v[18:19], v[36:37]
	v_fmac_f32_e32 v16, v20, v20
	v_fmac_f32_e32 v17, v22, v22
	v_add_f32_e32 v16, v16, v17
	v_mul_f32_e32 v17, v31, v31
	v_mul_f32_e32 v18, v29, v29
	v_fmac_f32_e32 v17, v30, v30
	v_fmac_f32_e32 v18, v28, v28
	v_add_f32_e32 v17, v17, v18
	v_add_f32_e32 v16, v16, v17
	v_add_f32_e32 v19, v38, v16
	v_mov_b32_e32 v34, v19
	s_nop 1
	v_permlane16_swap_b32_e32 v19, v34
	v_add_u32_e32 v32, 0xa0, v170
	s_waitcnt lgkmcnt(1)
	v_ashrrev_i32_e32 v33, 31, v32
	v_lshlrev_b64 v[32:33], 12, v[32:33]
	v_lshl_add_u64 v[16:17], s[28:29], 0, v[32:33]
	v_lshl_add_u64 v[32:33], v[168:169], 1, v[16:17]
	s_waitcnt lgkmcnt(0)
	v_add_f32_e32 v16, v19, v34
	v_mov_b32_e32 v17, v16
	s_nop 1
	v_permlane32_swap_b32_e32 v16, v17
	v_cvt_pk_bf16_f32 v18, v20, v21
	v_cvt_pk_bf16_f32 v19, v22, v23
	v_cvt_pk_bf16_f32 v20, v30, v31
	v_cvt_pk_bf16_f32 v21, v28, v29
	global_store_dwordx4 v[32:33], v[24:27], off
	global_store_dwordx4 v[32:33], v[18:21], off offset:256
	s_and_saveexec_b64 s[50:51], s[6:7]
	s_cbranch_execz .LBB0_519
	s_waitcnt lgkmcnt(0)
	v_add_f32_e32 v16, v16, v17
	ds_write_b32 v187, v16 offset:2560
.LBB0_519:
	s_or_b64 exec, exec, s[50:51]
	s_waitcnt vmcnt(7)
	v_lshlrev_b32_e32 v18, 16, v68
	v_and_b32_e32 v19, 0xffff0000, v68
	v_lshlrev_b32_e32 v20, 16, v69
	v_and_b32_e32 v21, 0xffff0000, v69
	v_lshlrev_b32_e32 v22, 16, v70
	v_and_b32_e32 v23, 0xffff0000, v70
	v_pk_add_f32 v[12:13], v[12:13], v[18:19]
	v_pk_add_f32 v[14:15], v[14:15], v[20:21]
	v_pk_add_f32 v[20:21], v[8:9], v[22:23]
	v_cvt_pk_bf16_f32 v8, v12, v13
	v_mul_f32_e32 v13, v13, v13
	v_lshlrev_b32_e32 v24, 16, v71
	v_and_b32_e32 v25, 0xffff0000, v71
	v_fmac_f32_e32 v13, v12, v12
	v_mul_f32_e32 v12, v15, v15
	v_pk_add_f32 v[18:19], v[10:11], v[24:25]
	v_fmac_f32_e32 v12, v14, v14
	v_cvt_pk_bf16_f32 v9, v14, v15
	v_add_f32_e32 v12, v13, v12
	v_mul_f32_e32 v13, v21, v21
	v_mul_f32_e32 v14, v19, v19
	v_fmac_f32_e32 v13, v20, v20
	v_fmac_f32_e32 v14, v18, v18
	v_add_f32_e32 v13, v13, v14
	v_add_f32_e32 v22, v12, v13
	s_waitcnt vmcnt(6)
	v_lshlrev_b32_e32 v12, 16, v64
	v_and_b32_e32 v13, 0xffff0000, v64
	v_lshlrev_b32_e32 v14, 16, v65
	v_and_b32_e32 v15, 0xffff0000, v65
	v_cvt_pk_bf16_f32 v11, v18, v19
	v_lshlrev_b32_e32 v18, 16, v66
	v_and_b32_e32 v19, 0xffff0000, v66
	v_pk_add_f32 v[6:7], v[6:7], v[14:15]
	v_pk_add_f32 v[4:5], v[4:5], v[12:13]
	v_cvt_pk_bf16_f32 v10, v20, v21
	v_lshlrev_b32_e32 v20, 16, v67
	v_and_b32_e32 v21, 0xffff0000, v67
	v_pk_add_f32 v[14:15], v[0:1], v[18:19]
	v_mul_f32_e32 v0, v5, v5
	v_mul_f32_e32 v1, v7, v7
	v_pk_add_f32 v[12:13], v[2:3], v[20:21]
	v_fmac_f32_e32 v0, v4, v4
	v_fmac_f32_e32 v1, v6, v6
	v_add_f32_e32 v0, v0, v1
	v_mul_f32_e32 v1, v15, v15
	v_mul_f32_e32 v2, v13, v13
	v_fmac_f32_e32 v1, v14, v14
	v_fmac_f32_e32 v2, v12, v12
	v_add_f32_e32 v1, v1, v2
	v_add_f32_e32 v0, v0, v1
	v_add_f32_e32 v3, v22, v0
	v_mov_b32_e32 v18, v3
	s_nop 1
	v_permlane16_swap_b32_e32 v3, v18
	v_add_u32_e32 v16, 0xb0, v170
	s_waitcnt lgkmcnt(1)
	v_ashrrev_i32_e32 v17, 31, v16
	v_lshlrev_b64 v[16:17], 12, v[16:17]
	v_lshl_add_u64 v[0:1], s[28:29], 0, v[16:17]
	v_lshl_add_u64 v[16:17], v[168:169], 1, v[0:1]
	s_waitcnt lgkmcnt(0)
	v_add_f32_e32 v0, v3, v18
	v_mov_b32_e32 v1, v0
	s_nop 1
	v_permlane32_swap_b32_e32 v0, v1
	v_cvt_pk_bf16_f32 v2, v4, v5
	v_cvt_pk_bf16_f32 v3, v6, v7
	v_cvt_pk_bf16_f32 v4, v14, v15
	v_cvt_pk_bf16_f32 v5, v12, v13
	global_store_dwordx4 v[16:17], v[8:11], off
	global_store_dwordx4 v[16:17], v[2:5], off offset:256
	s_and_saveexec_b64 s[50:51], s[6:7]
	s_cbranch_execz .LBB0_521
	s_waitcnt lgkmcnt(0)
	v_add_f32_e32 v0, v0, v1
	ds_write_b32 v187, v0 offset:2816

.LBB0_599:
	s_lshl_b32 s39, s46, 8
	v_add_u32_e32 v242, s39, v163
	v_add_u32_e32 v242, 64, v242
	v_ashrrev_i32_e32 v243, 31, v242
	v_lshlrev_b64 v[242:243], 5, v[242:243]
	v_lshl_add_u64 v[242:243], s[22:23], 0, v[242:243]
	global_load_dwordx4 v[192:195], v[242:243], off offset:-2048
	global_load_dwordx4 v[196:199], v[242:243], off offset:-2032
	global_load_dwordx4 v[200:203], v[242:243], off offset:-1536
	global_load_dwordx4 v[204:207], v[242:243], off offset:-1520
	global_load_dwordx4 v[208:211], v[242:243], off offset:-1024
	global_load_dwordx4 v[212:215], v[242:243], off offset:-1008
	global_load_dwordx4 v[216:219], v[242:243], off offset:-512
	global_load_dwordx4 v[220:223], v[242:243], off offset:-496
	global_load_dwordx4 v[224:227], v[242:243], off offset:2048
	global_load_dwordx4 v[228:231], v[242:243], off offset:2064
	global_load_dwordx4 v[232:235], v[242:243], off offset:2560
	global_load_dwordx4 v[236:239], v[242:243], off offset:2576
	v_max_f32_e32 v143, v127, v127
	v_max_f32_e32 v144, v126, v126
	v_max_f32_e32 v143, v144, v143
	v_max_f32_e32 v144, v123, v123
	v_max_f32_e32 v145, v122, v122
	v_max_f32_e32 v144, v145, v144
	v_max3_f32 v143, v124, v125, v143
	v_max3_f32 v144, v120, v121, v144
	v_and_b32_e32 v142, 64, v162
	v_max3_f32 v143, v143, s66, v144
	v_max_f32_e32 v144, v119, v119
	v_max_f32_e32 v145, v118, v118
	v_xor_b32_e32 v136, 16, v162
	v_add_u32_e32 v142, 64, v142
	v_max_f32_e32 v144, v145, v144
	v_max_f32_e32 v145, v115, v115
	v_max_f32_e32 v146, v114, v114
	v_cmp_lt_i32_e32 vcc, v136, v142
	v_max_f32_e32 v145, v146, v145
	v_max3_f32 v144, v116, v117, v144
	v_cndmask_b32_e32 v136, v162, v136, vcc
	v_max3_f32 v145, v112, v113, v145
	v_lshlrev_b32_e32 v136, 2, v136
	v_max3_f32 v143, v143, v144, v145
	v_mov_b32_e32 v144, v143
	s_nop 1
	v_permlane16_swap_b32_e32 v143, v144
	v_xor_b32_e32 v145, 32, v162
	v_cmp_lt_i32_e32 vcc, v145, v142
	s_nop 1
	v_cndmask_b32_e32 v142, v162, v145, vcc
	v_lshlrev_b32_e32 v165, 2, v142
	s_waitcnt lgkmcnt(0)
	v_max_f32_e32 v142, v144, v144
	v_max_f32_e32 v143, v143, v142
	v_mov_b32_e32 v144, v143
	s_nop 1
	v_permlane32_swap_b32_e32 v143, v144
	v_cmp_gt_u32_e32 vcc, 16, v162
	v_lshl_add_u32 v142, v162, 4, s62
	s_and_saveexec_b64 s[48:49], vcc
	s_cbranch_execz .LBB0_601
	s_waitcnt lgkmcnt(0)
	v_max_f32_e32 v144, v144, v144
	v_max_f32_e32 v143, v143, v143
	v_max_f32_e32 v143, v143, v144
	ds_write_b32 v142, v143
.LBB0_601:
	s_or_b64 exec, exec, s[48:49]
	v_max_f32_e32 v143, v111, v111
	s_waitcnt lgkmcnt(0)
	v_max_f32_e32 v144, v110, v110
	v_max_f32_e32 v143, v144, v143
	v_max_f32_e32 v144, v107, v107
	v_max_f32_e32 v145, v106, v106
	v_max_f32_e32 v144, v145, v144
	v_max3_f32 v143, v108, v109, v143
	v_max3_f32 v144, v104, v105, v144
	v_max3_f32 v143, v143, s66, v144
	v_max_f32_e32 v144, v103, v103
	v_max_f32_e32 v145, v102, v102
	v_max_f32_e32 v144, v145, v144
	v_max_f32_e32 v145, v99, v99
	v_max_f32_e32 v146, v98, v98
	v_max_f32_e32 v145, v146, v145
	v_max3_f32 v144, v100, v101, v144
	v_max3_f32 v145, v96, v97, v145
	v_max3_f32 v143, v143, v144, v145
	v_mov_b32_e32 v144, v143
	s_nop 1
	v_permlane16_swap_b32_e32 v143, v144
	s_waitcnt lgkmcnt(0)
	v_max_f32_e32 v144, v144, v144
	v_max_f32_e32 v143, v143, v144
	v_mov_b32_e32 v144, v143
	s_nop 1
	v_permlane32_swap_b32_e32 v143, v144
	s_and_saveexec_b64 s[48:49], vcc
	s_cbranch_execz .LBB0_603
	s_waitcnt lgkmcnt(0)
	v_max_f32_e32 v144, v144, v144
	v_max_f32_e32 v143, v143, v143
	v_max_f32_e32 v143, v143, v144
	ds_write_b32 v142, v143 offset:256
.LBB0_603:
	s_or_b64 exec, exec, s[48:49]
	v_max_f32_e32 v143, v95, v95
	s_waitcnt lgkmcnt(0)
	v_max_f32_e32 v144, v94, v94
	v_max_f32_e32 v143, v144, v143
	v_max_f32_e32 v144, v91, v91
	v_max_f32_e32 v145, v90, v90
	v_max_f32_e32 v144, v145, v144
	v_max3_f32 v143, v92, v93, v143
	v_max3_f32 v144, v88, v89, v144
	v_max3_f32 v143, v143, s66, v144
	v_max_f32_e32 v144, v87, v87
	v_max_f32_e32 v145, v86, v86
	v_max_f32_e32 v144, v145, v144
	v_max_f32_e32 v145, v83, v83
	v_max_f32_e32 v146, v82, v82
	v_max_f32_e32 v145, v146, v145
	v_max3_f32 v144, v84, v85, v144
	v_max3_f32 v145, v80, v81, v145
	v_max3_f32 v143, v143, v144, v145
	v_mov_b32_e32 v144, v143
	s_nop 1
	v_permlane16_swap_b32_e32 v143, v144
	s_waitcnt lgkmcnt(0)
	v_max_f32_e32 v144, v144, v144
	v_max_f32_e32 v143, v143, v144
	v_mov_b32_e32 v144, v143
	s_nop 1
	v_permlane32_swap_b32_e32 v143, v144
	s_and_saveexec_b64 s[48:49], vcc
	s_cbranch_execz .LBB0_605
	s_waitcnt lgkmcnt(0)
	v_max_f32_e32 v144, v144, v144
	v_max_f32_e32 v143, v143, v143
	v_max_f32_e32 v143, v143, v144
	ds_write_b32 v142, v143 offset:512
.LBB0_605:
	s_or_b64 exec, exec, s[48:49]
	v_max_f32_e32 v143, v79, v79
	s_waitcnt lgkmcnt(0)
	v_max_f32_e32 v144, v78, v78
	v_max_f32_e32 v143, v144, v143
	v_max_f32_e32 v144, v75, v75
	v_max_f32_e32 v145, v74, v74
	v_max_f32_e32 v144, v145, v144
	v_max3_f32 v143, v76, v77, v143
	v_max3_f32 v144, v72, v73, v144
	v_max3_f32 v143, v143, s66, v144
	v_max_f32_e32 v144, v71, v71
	v_max_f32_e32 v145, v70, v70
	v_max_f32_e32 v144, v145, v144
	v_max_f32_e32 v145, v67, v67
	v_max_f32_e32 v146, v66, v66
	v_max_f32_e32 v145, v146, v145
	v_max3_f32 v144, v68, v69, v144
	v_max3_f32 v145, v64, v65, v145
	v_max3_f32 v143, v143, v144, v145
	v_mov_b32_e32 v144, v143
	s_nop 1
	v_permlane16_swap_b32_e32 v143, v144
	s_waitcnt lgkmcnt(0)
	v_max_f32_e32 v144, v144, v144
	v_max_f32_e32 v143, v143, v144
	v_mov_b32_e32 v144, v143
	s_nop 1
	v_permlane32_swap_b32_e32 v143, v144
	s_and_saveexec_b64 s[48:49], vcc
	s_cbranch_execz .LBB0_607
	s_waitcnt lgkmcnt(0)
	v_max_f32_e32 v144, v144, v144
	v_max_f32_e32 v143, v143, v143
	v_max_f32_e32 v143, v143, v144
	ds_write_b32 v142, v143 offset:768
.LBB0_607:
	s_or_b64 exec, exec, s[48:49]
	v_max_f32_e32 v143, v63, v63
	s_waitcnt lgkmcnt(0)
	v_max_f32_e32 v144, v62, v62
	v_max_f32_e32 v143, v144, v143
	v_max_f32_e32 v144, v59, v59
	v_max_f32_e32 v145, v58, v58
	v_max_f32_e32 v144, v145, v144
	v_max3_f32 v143, v60, v61, v143
	v_max3_f32 v144, v56, v57, v144
	v_max3_f32 v143, v143, s66, v144
	v_max_f32_e32 v144, v55, v55
	v_max_f32_e32 v145, v54, v54
	v_max_f32_e32 v144, v145, v144
	v_max_f32_e32 v145, v51, v51
	v_max_f32_e32 v146, v50, v50
	v_max_f32_e32 v145, v146, v145
	v_max3_f32 v144, v52, v53, v144
	v_max3_f32 v145, v48, v49, v145
	v_max3_f32 v143, v143, v144, v145
	v_mov_b32_e32 v144, v143
	s_nop 1
	v_permlane16_swap_b32_e32 v143, v144
	s_waitcnt lgkmcnt(0)
	v_max_f32_e32 v144, v144, v144
	v_max_f32_e32 v143, v143, v144
	v_mov_b32_e32 v144, v143
	s_nop 1
	v_permlane32_swap_b32_e32 v143, v144
	s_and_saveexec_b64 s[48:49], vcc
	s_cbranch_execz .LBB0_609
	s_waitcnt lgkmcnt(0)
	v_max_f32_e32 v144, v144, v144
	v_max_f32_e32 v143, v143, v143
	v_max_f32_e32 v143, v143, v144
	ds_write_b32 v142, v143 offset:2048
.LBB0_609:
	s_or_b64 exec, exec, s[48:49]
	v_max_f32_e32 v143, v47, v47
	s_waitcnt lgkmcnt(0)
	v_max_f32_e32 v144, v46, v46
	v_max_f32_e32 v143, v144, v143
	v_max_f32_e32 v144, v43, v43
	v_max_f32_e32 v145, v42, v42
	v_max_f32_e32 v144, v145, v144
	v_max3_f32 v143, v44, v45, v143
	v_max3_f32 v144, v40, v41, v144
	v_max3_f32 v143, v143, s66, v144
	v_max_f32_e32 v144, v39, v39
	v_max_f32_e32 v145, v38, v38
	v_max_f32_e32 v144, v145, v144
	v_max_f32_e32 v145, v35, v35
	v_max_f32_e32 v146, v34, v34
	v_max_f32_e32 v145, v146, v145
	v_max3_f32 v144, v36, v37, v144
	v_max3_f32 v145, v32, v33, v145
	v_max3_f32 v143, v143, v144, v145
	v_mov_b32_e32 v144, v143
	s_nop 1
	v_permlane16_swap_b32_e32 v143, v144
	s_waitcnt lgkmcnt(0)
	v_max_f32_e32 v144, v144, v144
	v_max_f32_e32 v143, v143, v144
	v_mov_b32_e32 v144, v143
	s_nop 1
	v_permlane32_swap_b32_e32 v143, v144
	s_and_saveexec_b64 s[48:49], vcc
	s_cbranch_execz .LBB0_611
	s_waitcnt lgkmcnt(0)
	v_max_f32_e32 v144, v144, v144
	v_max_f32_e32 v143, v143, v143
	v_max_f32_e32 v143, v143, v144
	ds_write_b32 v142, v143 offset:2304
.LBB0_611:
	s_or_b64 exec, exec, s[48:49]
	v_max_f32_e32 v143, v31, v31
	s_waitcnt lgkmcnt(0)
	v_max_f32_e32 v144, v30, v30
	v_max_f32_e32 v143, v144, v143
	v_max_f32_e32 v144, v27, v27
	v_max_f32_e32 v145, v26, v26
	v_max_f32_e32 v144, v145, v144
	v_max3_f32 v143, v28, v29, v143
	v_max3_f32 v144, v24, v25, v144
	v_max3_f32 v143, v143, s66, v144
	v_max_f32_e32 v144, v23, v23
	v_max_f32_e32 v145, v22, v22
	v_max_f32_e32 v144, v145, v144
	v_max_f32_e32 v145, v19, v19
	v_max_f32_e32 v146, v18, v18
	v_max_f32_e32 v145, v146, v145
	v_max3_f32 v144, v20, v21, v144
	v_max3_f32 v145, v16, v17, v145
	v_max3_f32 v143, v143, v144, v145
	v_mov_b32_e32 v144, v143
	s_nop 1
	v_permlane16_swap_b32_e32 v143, v144
	s_waitcnt lgkmcnt(0)
	v_max_f32_e32 v144, v144, v144
	v_max_f32_e32 v143, v143, v144
	v_mov_b32_e32 v144, v143
	s_nop 1
	v_permlane32_swap_b32_e32 v143, v144
	s_and_saveexec_b64 s[48:49], vcc
	s_cbranch_execz .LBB0_613
	s_waitcnt lgkmcnt(0)
	v_max_f32_e32 v144, v144, v144
	v_max_f32_e32 v143, v143, v143
	v_max_f32_e32 v143, v143, v144
	ds_write_b32 v142, v143 offset:2560
.LBB0_613:
	s_or_b64 exec, exec, s[48:49]
	v_max_f32_e32 v143, v15, v15
	s_waitcnt lgkmcnt(0)
	v_max_f32_e32 v144, v14, v14
	v_max_f32_e32 v143, v144, v143
	v_max_f32_e32 v144, v11, v11
	v_max_f32_e32 v145, v10, v10
	v_max_f32_e32 v144, v145, v144
	v_max3_f32 v143, v12, v13, v143
	v_max3_f32 v144, v8, v9, v144
	v_max3_f32 v143, v143, s66, v144
	v_max_f32_e32 v144, v7, v7
	v_max_f32_e32 v145, v6, v6
	v_max_f32_e32 v144, v145, v144
	v_max_f32_e32 v145, v3, v3
	v_max_f32_e32 v146, v2, v2
	v_max_f32_e32 v145, v146, v145
	v_max3_f32 v144, v4, v5, v144
	v_max3_f32 v145, v0, v1, v145
	v_max3_f32 v143, v143, v144, v145
	v_mov_b32_e32 v144, v143
	s_nop 1
	v_permlane16_swap_b32_e32 v143, v144
	s_waitcnt lgkmcnt(0)
	v_max_f32_e32 v144, v144, v144
	v_max_f32_e32 v143, v143, v144
	v_mov_b32_e32 v144, v143
	s_nop 1
	v_permlane32_swap_b32_e32 v143, v144
	s_and_saveexec_b64 s[48:49], vcc
	s_cbranch_execz .LBB0_615
	s_waitcnt lgkmcnt(0)
	v_max_f32_e32 v144, v144, v144
	v_max_f32_e32 v143, v143, v143
	v_max_f32_e32 v143, v143, v144
	ds_write_b32 v142, v143 offset:2816
.LBB0_615:
	s_or_b64 exec, exec, s[48:49]
	s_lshl_b32 s39, s46, 8
	v_add_u32_e32 v142, s39, v163
	v_ashrrev_i32_e32 v143, 31, v142
	s_waitcnt lgkmcnt(0)
	v_lshlrev_b64 v[144:145], 5, v[142:143]
	s_waitcnt lgkmcnt(0)
	s_barrier
	v_lshl_add_u64 v[148:149], s[22:23], 0, v[144:145]
	s_waitcnt vmcnt(0)
	v_mov_b32_e32 v144, v192
	v_mov_b32_e32 v145, v193
	v_mov_b32_e32 v146, v194
	v_mov_b32_e32 v147, v195
	v_mov_b32_e32 v148, v196
	v_mov_b32_e32 v149, v197
	v_mov_b32_e32 v150, v198
	v_mov_b32_e32 v151, v199
	global_load_dwordx4 v[192:195], v[242:243], off offset:3072
	global_load_dwordx4 v[196:199], v[242:243], off offset:3088
	v_lshl_add_u32 v152, v163, 4, 0
	v_add_u32_e32 v152, 0x20000, v152
	ds_read_b128 v[152:155], v152
	v_mov_b32_e32 v156, v115
	s_waitcnt lgkmcnt(0)
	v_max_f32_e32 v115, v155, v155
	v_mov_b32_e32 v166, v144
	v_mov_b32_e32 v167, v148
	v_mov_b32_e32 v148, v145
	v_mov_b32_e32 v144, v146
	v_mov_b32_e32 v145, v150
	v_mov_b32_e32 v150, v147
	v_pk_add_f32 v[146:147], v[166:167], v[148:149]
	v_pk_add_f32 v[144:145], v[144:145], v[150:151]
	s_nop 0
	v_pk_add_f32 v[144:145], v[146:147], v[144:145]
	s_nop 0
	v_add_f32_e32 v144, v144, v145
	v_fmamk_f32 v144, v144, 0x3a000000, v164
	v_rsq_f32_e32 v144, v144
	v_max_f32_e32 v145, v154, v154
	v_max_f32_e32 v115, v145, v115
	v_max3_f32 v157, v152, v153, v115
	v_mul_f32_e32 v144, 0x3d8293ee, v144
	v_pk_mul_f32 v[146:147], v[156:157], v[144:145] op_sel_hi:[1,0]
	s_nop 0
	v_fma_f32 v115, v124, v144, -v147
	v_fma_f32 v124, v125, v144, -v147
	v_fma_f32 v125, v126, v144, -v147
	v_fma_f32 v127, v127, v144, -v147
	v_fma_f32 v145, v120, v144, -v147
	v_fma_f32 v148, v121, v144, -v147
	v_fma_f32 v149, v122, v144, -v147
	v_fma_f32 v150, v123, v144, -v147
	v_exp_f32_e32 v120, v115
	v_exp_f32_e32 v121, v124
	v_exp_f32_e32 v126, v125
	v_exp_f32_e32 v127, v127
	v_fma_f32 v116, v116, v144, -v147
	v_fma_f32 v117, v117, v144, -v147
	v_fma_f32 v118, v118, v144, -v147
	v_fma_f32 v119, v119, v144, -v147
	v_fma_f32 v151, v112, v144, -v147
	v_fma_f32 v152, v113, v144, -v147
	v_fma_f32 v153, v114, v144, -v147
	v_exp_f32_e32 v122, v145
	v_exp_f32_e32 v123, v148
	v_exp_f32_e32 v144, v149
	v_exp_f32_e32 v145, v150
	v_sub_f32_e32 v146, v146, v147
	v_exp_f32_e32 v112, v116
	v_exp_f32_e32 v113, v117
	v_exp_f32_e32 v116, v118
	v_exp_f32_e32 v117, v119
	v_exp_f32_e32 v114, v151
	v_exp_f32_e32 v115, v152
	v_exp_f32_e32 v118, v153
	v_exp_f32_e32 v119, v146
	v_add_f32_e32 v124, v120, v121
	v_add_f32_e32 v125, v126, v127
	v_add_f32_e32 v146, v122, v123
	v_add_f32_e32 v147, v144, v145
	v_add_f32_e32 v124, v124, v125
	v_add_f32_e32 v148, v112, v113
	v_add_f32_e32 v149, v116, v117
	v_add_f32_e32 v125, v146, v147
	v_add_f32_e32 v124, 0, v124
	v_add_f32_e32 v150, v114, v115
	v_add_f32_e32 v151, v118, v119
	v_add_f32_e32 v146, v148, v149
	v_add_f32_e32 v124, v125, v124
	v_add_f32_e32 v124, v146, v124
	v_add_f32_e32 v125, v150, v151
	v_add_f32_e32 v124, v125, v124
	v_mov_b32_e32 v125, v124
	s_nop 1
	v_permlane16_swap_b32_e32 v124, v125
	s_waitcnt lgkmcnt(0)
	v_add_f32_e32 v124, v124, v125
	v_mov_b32_e32 v125, v124
	s_nop 1
	v_permlane32_swap_b32_e32 v124, v125
	s_and_saveexec_b64 s[46:47], vcc
	s_cbranch_execz .LBB0_617
	v_lshlrev_b32_e32 v146, 2, v163
	v_lshl_add_u32 v146, v146, 2, s63
	s_waitcnt lgkmcnt(0)
	v_add_f32_e32 v124, v124, v125
	ds_write_b32 v146, v124
.LBB0_617:
	s_or_b64 exec, exec, s[46:47]
	v_or_b32_e32 v166, 16, v163
	v_add_u32_e32 v124, s39, v166
	s_waitcnt lgkmcnt(0)
	v_ashrrev_i32_e32 v125, 31, v124
	v_lshlrev_b64 v[146:147], 5, v[124:125]
	v_lshl_add_u64 v[150:151], s[22:23], 0, v[146:147]
	s_waitcnt vmcnt(2)
	v_mov_b32_e32 v146, v200
	v_mov_b32_e32 v147, v201
	v_mov_b32_e32 v148, v202
	v_mov_b32_e32 v149, v203
	v_mov_b32_e32 v150, v204
	v_mov_b32_e32 v151, v205
	v_mov_b32_e32 v152, v206
	v_mov_b32_e32 v153, v207
	global_load_dwordx4 v[200:203], v[242:243], off offset:3584
	global_load_dwordx4 v[204:207], v[242:243], off offset:3600
	v_lshl_add_u32 v154, v166, 4, 0
	v_add_u32_e32 v154, 0x20000, v154
	ds_read_b128 v[154:157], v154
	v_mov_b32_e32 v168, v99
	s_waitcnt lgkmcnt(0)
	v_max_f32_e32 v99, v157, v157
	v_mov_b32_e32 v170, v146
	v_mov_b32_e32 v171, v150
	v_mov_b32_e32 v150, v147
	v_mov_b32_e32 v146, v148
	v_mov_b32_e32 v147, v152
	v_mov_b32_e32 v152, v149
	v_pk_add_f32 v[148:149], v[170:171], v[150:151]
	v_pk_add_f32 v[146:147], v[146:147], v[152:153]
	s_nop 0
	v_pk_add_f32 v[146:147], v[148:149], v[146:147]
	s_nop 0
	v_add_f32_e32 v146, v146, v147
	v_fmamk_f32 v146, v146, 0x3a000000, v164
	v_rsq_f32_e32 v146, v146
	v_max_f32_e32 v147, v156, v156
	v_max_f32_e32 v99, v147, v99
	v_max3_f32 v169, v154, v155, v99
	v_mul_f32_e32 v146, 0x3d8293ee, v146
	v_pk_mul_f32 v[148:149], v[168:169], v[146:147] op_sel_hi:[1,0]
	s_nop 0
	v_fma_f32 v99, v108, v146, -v149
	v_fma_f32 v109, v109, v146, -v149
	v_fma_f32 v110, v110, v146, -v149
	v_fma_f32 v111, v111, v146, -v149
	v_fma_f32 v104, v104, v146, -v149
	v_fma_f32 v105, v105, v146, -v149
	v_fma_f32 v150, v106, v146, -v149
	v_fma_f32 v151, v107, v146, -v149
	v_fma_f32 v100, v100, v146, -v149
	v_fma_f32 v101, v101, v146, -v149
	v_fma_f32 v102, v102, v146, -v149
	v_fma_f32 v103, v103, v146, -v149
	v_fma_f32 v96, v96, v146, -v149
	v_fma_f32 v97, v97, v146, -v149
	v_fma_f32 v152, v98, v146, -v149
	v_exp_f32_e32 v108, v99
	v_exp_f32_e32 v109, v109
	v_exp_f32_e32 v146, v110
	v_exp_f32_e32 v147, v111
	v_exp_f32_e32 v106, v104
	v_exp_f32_e32 v107, v105
	v_exp_f32_e32 v110, v150
	v_exp_f32_e32 v111, v151
	v_sub_f32_e32 v148, v148, v149
	v_exp_f32_e32 v100, v100
	v_exp_f32_e32 v101, v101
	v_exp_f32_e32 v104, v102
	v_exp_f32_e32 v105, v103
	v_exp_f32_e32 v98, v96
	v_exp_f32_e32 v99, v97
	v_exp_f32_e32 v102, v152
	v_exp_f32_e32 v103, v148
	v_add_f32_e32 v96, v108, v109
	v_add_f32_e32 v97, v146, v147
	v_add_f32_e32 v148, v106, v107
	v_add_f32_e32 v149, v110, v111
	v_add_f32_e32 v96, v96, v97
	v_add_f32_e32 v150, v100, v101
	v_add_f32_e32 v151, v104, v105
	v_add_f32_e32 v97, v148, v149
	v_add_f32_e32 v96, 0, v96
	v_add_f32_e32 v152, v98, v99
	v_add_f32_e32 v153, v102, v103
	v_add_f32_e32 v148, v150, v151
	v_add_f32_e32 v96, v97, v96
	v_add_f32_e32 v96, v148, v96
	v_add_f32_e32 v97, v152, v153
	v_add_f32_e32 v96, v97, v96
	v_mov_b32_e32 v97, v96
	s_nop 1
	v_permlane16_swap_b32_e32 v96, v97
	s_waitcnt lgkmcnt(0)
	v_add_f32_e32 v96, v96, v97
	v_mov_b32_e32 v97, v96
	s_nop 1
	v_permlane32_swap_b32_e32 v96, v97
	s_and_saveexec_b64 s[46:47], vcc
	s_cbranch_execz .LBB0_619
	v_lshlrev_b32_e32 v148, 2, v166
	v_lshl_add_u32 v148, v148, 2, s63
	s_waitcnt lgkmcnt(0)
	v_add_f32_e32 v96, v96, v97
	ds_write_b32 v148, v96
.LBB0_619:
	s_or_b64 exec, exec, s[46:47]
	v_or_b32_e32 v167, 32, v163
	v_add_u32_e32 v96, s39, v167
	s_waitcnt lgkmcnt(0)
	v_ashrrev_i32_e32 v97, 31, v96
	v_lshlrev_b64 v[148:149], 5, v[96:97]
	v_lshl_add_u64 v[152:153], s[22:23], 0, v[148:149]
	v_mov_b32_e32 v148, v208
	v_mov_b32_e32 v149, v209
	v_mov_b32_e32 v150, v210
	v_mov_b32_e32 v151, v211
	v_mov_b32_e32 v152, v212
	v_mov_b32_e32 v153, v213
	v_mov_b32_e32 v154, v214
	v_mov_b32_e32 v155, v215
	v_lshl_add_u32 v156, v167, 4, 0
	v_add_u32_e32 v156, 0x20000, v156
	ds_read_b128 v[168:171], v156
	v_mov_b32_e32 v156, v83
	s_waitcnt lgkmcnt(0)
	v_max_f32_e32 v83, v171, v171
	v_mov_b32_e32 v172, v148
	v_mov_b32_e32 v173, v152
	v_mov_b32_e32 v152, v149
	v_mov_b32_e32 v148, v150
	v_mov_b32_e32 v149, v154
	v_mov_b32_e32 v154, v151
	v_pk_add_f32 v[150:151], v[172:173], v[152:153]
	v_pk_add_f32 v[148:149], v[148:149], v[154:155]
	s_nop 0
	v_pk_add_f32 v[148:149], v[150:151], v[148:149]
	s_nop 0
	v_add_f32_e32 v148, v148, v149
	v_fmamk_f32 v148, v148, 0x3a000000, v164
	v_rsq_f32_e32 v148, v148
	v_max_f32_e32 v149, v170, v170
	v_max_f32_e32 v83, v149, v83
	v_max3_f32 v157, v168, v169, v83
	v_mul_f32_e32 v148, 0x3d8293ee, v148
	v_pk_mul_f32 v[150:151], v[156:157], v[148:149] op_sel_hi:[1,0]
	s_nop 0
	v_fma_f32 v83, v92, v148, -v151
	v_fma_f32 v92, v93, v148, -v151
	v_fma_f32 v93, v94, v148, -v151
	v_fma_f32 v94, v95, v148, -v151
	v_fma_f32 v95, v88, v148, -v151
	v_fma_f32 v149, v89, v148, -v151
	v_fma_f32 v152, v90, v148, -v151
	v_fma_f32 v153, v91, v148, -v151
	v_exp_f32_e32 v88, v83
	v_exp_f32_e32 v89, v92
	v_exp_f32_e32 v92, v93
	v_exp_f32_e32 v93, v94
	v_fma_f32 v84, v84, v148, -v151
	v_fma_f32 v85, v85, v148, -v151
	v_fma_f32 v86, v86, v148, -v151
	v_fma_f32 v87, v87, v148, -v151
	v_fma_f32 v154, v80, v148, -v151
	v_fma_f32 v155, v81, v148, -v151
	v_fma_f32 v156, v82, v148, -v151
	v_exp_f32_e32 v90, v95
	v_exp_f32_e32 v91, v149
	v_exp_f32_e32 v148, v152
	v_exp_f32_e32 v149, v153
	v_sub_f32_e32 v150, v150, v151
	v_exp_f32_e32 v80, v84
	v_exp_f32_e32 v81, v85
	v_exp_f32_e32 v84, v86
	v_exp_f32_e32 v85, v87
	v_exp_f32_e32 v82, v154
	v_exp_f32_e32 v83, v155
	v_exp_f32_e32 v86, v156
	v_exp_f32_e32 v87, v150
	v_add_f32_e32 v94, v88, v89
	v_add_f32_e32 v95, v92, v93
	v_add_f32_e32 v150, v90, v91
	v_add_f32_e32 v151, v148, v149
	v_add_f32_e32 v94, v94, v95
	v_add_f32_e32 v152, v80, v81
	v_add_f32_e32 v153, v84, v85
	v_add_f32_e32 v95, v150, v151
	v_add_f32_e32 v94, 0, v94
	v_add_f32_e32 v154, v82, v83
	v_add_f32_e32 v155, v86, v87
	v_add_f32_e32 v150, v152, v153
	v_add_f32_e32 v94, v95, v94
	v_add_f32_e32 v94, v150, v94
	v_add_f32_e32 v95, v154, v155
	v_add_f32_e32 v94, v95, v94
	v_mov_b32_e32 v95, v94
	s_nop 1
	v_permlane16_swap_b32_e32 v94, v95
	s_waitcnt lgkmcnt(0)
	v_add_f32_e32 v94, v94, v95
	v_mov_b32_e32 v95, v94
	s_nop 1
	v_permlane32_swap_b32_e32 v94, v95
	s_and_saveexec_b64 s[46:47], vcc
	s_cbranch_execz .LBB0_621
	v_lshlrev_b32_e32 v150, 2, v167
	v_lshl_add_u32 v150, v150, 2, s63
	s_waitcnt lgkmcnt(0)
	v_add_f32_e32 v94, v94, v95
	ds_write_b32 v150, v94
.LBB0_621:
	s_or_b64 exec, exec, s[46:47]
	v_or_b32_e32 v168, 48, v163
	v_add_u32_e32 v94, s39, v168
	s_waitcnt lgkmcnt(0)
	v_ashrrev_i32_e32 v95, 31, v94
	v_lshlrev_b64 v[150:151], 5, v[94:95]
	v_lshl_add_u64 v[154:155], s[22:23], 0, v[150:151]
	v_mov_b32_e32 v150, v216
	v_mov_b32_e32 v151, v217
	v_mov_b32_e32 v152, v218
	v_mov_b32_e32 v153, v219
	v_mov_b32_e32 v154, v220
	v_mov_b32_e32 v155, v221
	v_mov_b32_e32 v156, v222
	v_mov_b32_e32 v157, v223
	v_lshl_add_u32 v169, v168, 4, 0
	v_add_u32_e32 v169, 0x20000, v169
	ds_read_b128 v[170:173], v169
	v_mov_b32_e32 v176, v67
	s_waitcnt lgkmcnt(0)
	v_max_f32_e32 v67, v173, v173
	v_mov_b32_e32 v178, v150
	v_mov_b32_e32 v179, v154
	v_mov_b32_e32 v154, v151
	v_mov_b32_e32 v150, v152
	v_mov_b32_e32 v151, v156
	v_mov_b32_e32 v156, v153
	v_pk_add_f32 v[152:153], v[178:179], v[154:155]
	v_pk_add_f32 v[150:151], v[150:151], v[156:157]
	s_nop 0
	v_pk_add_f32 v[150:151], v[152:153], v[150:151]
	s_nop 0
	v_add_f32_e32 v150, v150, v151
	v_fmamk_f32 v150, v150, 0x3a000000, v164
	v_rsq_f32_e32 v150, v150
	v_max_f32_e32 v151, v172, v172
	v_max_f32_e32 v67, v151, v67
	v_max3_f32 v177, v170, v171, v67
	v_mul_f32_e32 v150, 0x3d8293ee, v150
	v_pk_mul_f32 v[152:153], v[176:177], v[150:151] op_sel_hi:[1,0]
	s_nop 0
	v_fma_f32 v67, v76, v150, -v153
	v_fma_f32 v77, v77, v150, -v153
	v_fma_f32 v78, v78, v150, -v153
	v_fma_f32 v79, v79, v150, -v153
	v_fma_f32 v72, v72, v150, -v153
	v_fma_f32 v73, v73, v150, -v153
	v_fma_f32 v154, v74, v150, -v153
	v_fma_f32 v155, v75, v150, -v153
	v_fma_f32 v68, v68, v150, -v153
	v_fma_f32 v69, v69, v150, -v153
	v_fma_f32 v70, v70, v150, -v153
	v_fma_f32 v71, v71, v150, -v153
	v_fma_f32 v64, v64, v150, -v153
	v_fma_f32 v65, v65, v150, -v153
	v_fma_f32 v156, v66, v150, -v153
	v_exp_f32_e32 v76, v67
	v_exp_f32_e32 v77, v77
	v_exp_f32_e32 v150, v78
	v_exp_f32_e32 v151, v79
	v_exp_f32_e32 v74, v72
	v_exp_f32_e32 v75, v73
	v_exp_f32_e32 v78, v154
	v_exp_f32_e32 v79, v155
	v_sub_f32_e32 v152, v152, v153
	v_exp_f32_e32 v68, v68
	v_exp_f32_e32 v69, v69
	v_exp_f32_e32 v72, v70
	v_exp_f32_e32 v73, v71
	v_exp_f32_e32 v66, v64
	v_exp_f32_e32 v67, v65
	v_exp_f32_e32 v70, v156
	v_exp_f32_e32 v71, v152
	v_add_f32_e32 v64, v76, v77
	v_add_f32_e32 v65, v150, v151
	v_add_f32_e32 v152, v74, v75
	v_add_f32_e32 v153, v78, v79
	v_add_f32_e32 v64, v64, v65
	v_add_f32_e32 v154, v68, v69
	v_add_f32_e32 v155, v72, v73
	v_add_f32_e32 v65, v152, v153
	v_add_f32_e32 v64, 0, v64
	v_add_f32_e32 v156, v66, v67
	v_add_f32_e32 v157, v70, v71
	v_add_f32_e32 v152, v154, v155
	v_add_f32_e32 v64, v65, v64
	v_add_f32_e32 v64, v152, v64
	v_add_f32_e32 v65, v156, v157
	v_add_f32_e32 v64, v65, v64
	v_mov_b32_e32 v65, v64
	s_nop 1
	v_permlane16_swap_b32_e32 v64, v65
	s_waitcnt lgkmcnt(0)
	v_add_f32_e32 v64, v64, v65
	v_mov_b32_e32 v65, v64
	s_nop 1
	v_permlane32_swap_b32_e32 v64, v65
	s_and_saveexec_b64 s[46:47], vcc
	s_cbranch_execz .LBB0_623
	v_lshlrev_b32_e32 v152, 2, v168
	v_lshl_add_u32 v152, v152, 2, s63
	s_waitcnt lgkmcnt(0)
	v_add_f32_e32 v64, v64, v65
	ds_write_b32 v152, v64
.LBB0_623:
	s_or_b64 exec, exec, s[46:47]
	v_add_u32_e32 v169, 0x80, v163
	v_add_u32_e32 v64, s39, v169
	s_waitcnt lgkmcnt(0)
	v_ashrrev_i32_e32 v65, 31, v64
	v_lshlrev_b64 v[152:153], 5, v[64:65]
	v_lshl_add_u64 v[156:157], s[22:23], 0, v[152:153]
	v_mov_b32_e32 v152, v224
	v_mov_b32_e32 v153, v225
	v_mov_b32_e32 v154, v226
	v_mov_b32_e32 v155, v227
	v_mov_b32_e32 v170, v228
	v_mov_b32_e32 v171, v229
	v_mov_b32_e32 v172, v230
	v_mov_b32_e32 v173, v231
	v_lshl_add_u32 v156, v169, 4, 0
	v_add_u32_e32 v156, 0x20000, v156
	ds_read_b128 v[176:179], v156
	v_mov_b32_e32 v156, v51
	s_waitcnt lgkmcnt(0)
	v_max_f32_e32 v51, v179, v179
	v_mov_b32_e32 v180, v152
	v_mov_b32_e32 v181, v170
	v_mov_b32_e32 v170, v153
	v_mov_b32_e32 v152, v154
	v_mov_b32_e32 v153, v172
	v_mov_b32_e32 v172, v155
	v_pk_add_f32 v[154:155], v[180:181], v[170:171]
	v_pk_add_f32 v[152:153], v[152:153], v[172:173]
	s_nop 0
	v_pk_add_f32 v[152:153], v[154:155], v[152:153]
	s_nop 0
	v_add_f32_e32 v152, v152, v153
	v_fmamk_f32 v152, v152, 0x3a000000, v164
	v_rsq_f32_e32 v152, v152
	v_max_f32_e32 v153, v178, v178
	v_max_f32_e32 v51, v153, v51
	v_max3_f32 v157, v176, v177, v51
	v_mul_f32_e32 v152, 0x3d8293ee, v152
	v_pk_mul_f32 v[154:155], v[156:157], v[152:153] op_sel_hi:[1,0]
	s_nop 0
	v_fma_f32 v51, v60, v152, -v155
	v_fma_f32 v60, v61, v152, -v155
	v_fma_f32 v61, v62, v152, -v155
	v_fma_f32 v62, v63, v152, -v155
	v_fma_f32 v63, v56, v152, -v155
	v_fma_f32 v153, v57, v152, -v155
	v_fma_f32 v156, v58, v152, -v155
	v_fma_f32 v157, v59, v152, -v155
	v_exp_f32_e32 v56, v51
	v_exp_f32_e32 v57, v60
	v_exp_f32_e32 v60, v61
	v_exp_f32_e32 v61, v62
	v_fma_f32 v52, v52, v152, -v155
	v_fma_f32 v53, v53, v152, -v155
	v_fma_f32 v54, v54, v152, -v155
	v_fma_f32 v55, v55, v152, -v155
	v_fma_f32 v170, v48, v152, -v155
	v_fma_f32 v171, v49, v152, -v155
	v_fma_f32 v172, v50, v152, -v155
	v_exp_f32_e32 v58, v63
	v_exp_f32_e32 v59, v153
	v_exp_f32_e32 v152, v156
	v_exp_f32_e32 v153, v157
	v_sub_f32_e32 v154, v154, v155
	v_exp_f32_e32 v48, v52
	v_exp_f32_e32 v49, v53
	v_exp_f32_e32 v52, v54
	v_exp_f32_e32 v53, v55
	v_exp_f32_e32 v50, v170
	v_exp_f32_e32 v51, v171
	v_exp_f32_e32 v54, v172
	v_exp_f32_e32 v55, v154
	v_add_f32_e32 v62, v56, v57
	v_add_f32_e32 v63, v60, v61
	v_add_f32_e32 v154, v58, v59
	v_add_f32_e32 v155, v152, v153
	v_add_f32_e32 v62, v62, v63
	v_add_f32_e32 v156, v48, v49
	v_add_f32_e32 v157, v52, v53
	v_add_f32_e32 v63, v154, v155
	v_add_f32_e32 v62, 0, v62
	v_add_f32_e32 v170, v50, v51
	v_add_f32_e32 v171, v54, v55
	v_add_f32_e32 v154, v156, v157
	v_add_f32_e32 v62, v63, v62
	v_add_f32_e32 v62, v154, v62
	v_add_f32_e32 v63, v170, v171
	v_add_f32_e32 v62, v63, v62
	v_mov_b32_e32 v63, v62
	s_nop 1
	v_permlane16_swap_b32_e32 v62, v63
	s_waitcnt lgkmcnt(0)
	v_add_f32_e32 v62, v62, v63
	v_mov_b32_e32 v63, v62
	s_nop 1
	v_permlane32_swap_b32_e32 v62, v63
	s_and_saveexec_b64 s[46:47], vcc
	s_cbranch_execz .LBB0_625
	v_lshlrev_b32_e32 v154, 2, v169
	v_lshl_add_u32 v154, v154, 2, s63
	s_waitcnt lgkmcnt(0)
	v_add_f32_e32 v62, v62, v63
	ds_write_b32 v154, v62
.LBB0_625:
	s_or_b64 exec, exec, s[46:47]
	v_add_u32_e32 v170, 0x90, v163
	v_add_u32_e32 v62, s39, v170
	s_waitcnt lgkmcnt(0)
	v_ashrrev_i32_e32 v63, 31, v62
	v_lshlrev_b64 v[154:155], 5, v[62:63]
	v_lshl_add_u64 v[172:173], s[22:23], 0, v[154:155]
	v_mov_b32_e32 v154, v232
	v_mov_b32_e32 v155, v233
	v_mov_b32_e32 v156, v234
	v_mov_b32_e32 v157, v235
	v_mov_b32_e32 v176, v236
	v_mov_b32_e32 v177, v237
	v_mov_b32_e32 v178, v238
	v_mov_b32_e32 v179, v239
	v_lshl_add_u32 v171, v170, 4, 0
	v_add_u32_e32 v171, 0x20000, v171
	ds_read_b128 v[180:183], v171
	v_mov_b32_e32 v172, v35
	s_waitcnt lgkmcnt(0)
	v_max_f32_e32 v35, v183, v183
	v_mov_b32_e32 v184, v154
	v_mov_b32_e32 v185, v176
	v_mov_b32_e32 v176, v155
	v_mov_b32_e32 v154, v156
	v_mov_b32_e32 v155, v178
	v_mov_b32_e32 v178, v157
	v_pk_add_f32 v[156:157], v[184:185], v[176:177]
	v_pk_add_f32 v[154:155], v[154:155], v[178:179]
	s_nop 0
	v_pk_add_f32 v[154:155], v[156:157], v[154:155]
	s_nop 0
	v_add_f32_e32 v154, v154, v155
	v_fmamk_f32 v154, v154, 0x3a000000, v164
	v_rsq_f32_e32 v154, v154
	v_max_f32_e32 v155, v182, v182
	v_max_f32_e32 v35, v155, v35
	v_max3_f32 v173, v180, v181, v35
	v_mul_f32_e32 v154, 0x3d8293ee, v154
	v_pk_mul_f32 v[156:157], v[172:173], v[154:155] op_sel_hi:[1,0]
	s_nop 0
	v_fma_f32 v35, v44, v154, -v157
	v_fma_f32 v45, v45, v154, -v157
	v_fma_f32 v46, v46, v154, -v157
	v_fma_f32 v47, v47, v154, -v157
	v_fma_f32 v40, v40, v154, -v157
	v_fma_f32 v41, v41, v154, -v157
	v_fma_f32 v171, v42, v154, -v157
	v_fma_f32 v172, v43, v154, -v157
	v_fma_f32 v36, v36, v154, -v157
	v_fma_f32 v37, v37, v154, -v157
	v_fma_f32 v38, v38, v154, -v157
	v_fma_f32 v39, v39, v154, -v157
	v_fma_f32 v32, v32, v154, -v157
	v_fma_f32 v33, v33, v154, -v157
	v_fma_f32 v173, v34, v154, -v157
	v_exp_f32_e32 v44, v35
	v_exp_f32_e32 v45, v45
	v_exp_f32_e32 v154, v46
	v_exp_f32_e32 v155, v47
	v_exp_f32_e32 v42, v40
	v_exp_f32_e32 v43, v41
	v_exp_f32_e32 v46, v171
	v_exp_f32_e32 v47, v172
	v_sub_f32_e32 v156, v156, v157
	v_exp_f32_e32 v36, v36
	v_exp_f32_e32 v37, v37
	v_exp_f32_e32 v40, v38
	v_exp_f32_e32 v41, v39
	v_exp_f32_e32 v34, v32
	v_exp_f32_e32 v35, v33
	v_exp_f32_e32 v38, v173
	v_exp_f32_e32 v39, v156
	v_add_f32_e32 v32, v44, v45
	v_add_f32_e32 v33, v154, v155
	v_add_f32_e32 v156, v42, v43
	v_add_f32_e32 v157, v46, v47
	v_add_f32_e32 v32, v32, v33
	v_add_f32_e32 v171, v36, v37
	v_add_f32_e32 v172, v40, v41
	v_add_f32_e32 v33, v156, v157
	v_add_f32_e32 v32, 0, v32
	v_add_f32_e32 v173, v34, v35
	v_add_f32_e32 v176, v38, v39
	v_add_f32_e32 v156, v171, v172
	v_add_f32_e32 v32, v33, v32
	v_add_f32_e32 v32, v156, v32
	v_add_f32_e32 v33, v173, v176
	v_add_f32_e32 v32, v33, v32
	v_mov_b32_e32 v33, v32
	s_nop 1
	v_permlane16_swap_b32_e32 v32, v33
	s_waitcnt lgkmcnt(0)
	v_add_f32_e32 v32, v32, v33
	v_mov_b32_e32 v33, v32
	s_nop 1
	v_permlane32_swap_b32_e32 v32, v33
	s_and_saveexec_b64 s[46:47], vcc
	s_cbranch_execz .LBB0_627
	v_lshlrev_b32_e32 v156, 2, v170
	v_lshl_add_u32 v156, v156, 2, s63
	s_waitcnt lgkmcnt(0)
	v_add_f32_e32 v32, v32, v33
	ds_write_b32 v156, v32
.LBB0_627:
	s_or_b64 exec, exec, s[46:47]
	v_add_u32_e32 v171, 0xa0, v163
	v_add_u32_e32 v32, s39, v171
	s_waitcnt lgkmcnt(0)
	v_ashrrev_i32_e32 v33, 31, v32
	v_lshlrev_b64 v[156:157], 5, v[32:33]
	v_lshl_add_u64 v[156:157], s[22:23], 0, v[156:157]
	s_waitcnt vmcnt(2)
	v_mov_b32_e32 v176, v192
	v_mov_b32_e32 v177, v193
	v_mov_b32_e32 v178, v194
	v_mov_b32_e32 v179, v195
	v_mov_b32_e32 v180, v196
	v_mov_b32_e32 v181, v197
	v_mov_b32_e32 v182, v198
	v_mov_b32_e32 v183, v199
	v_lshl_add_u32 v156, v171, 4, 0
	v_add_u32_e32 v156, 0x20000, v156
	ds_read_b128 v[184:187], v156
	v_mov_b32_e32 v156, v19
	s_waitcnt lgkmcnt(0)
	v_max_f32_e32 v19, v187, v187
	v_mov_b32_e32 v172, v176
	v_mov_b32_e32 v173, v180
	v_mov_b32_e32 v180, v177
	v_mov_b32_e32 v176, v178
	v_mov_b32_e32 v177, v182
	v_mov_b32_e32 v182, v179
	v_pk_add_f32 v[172:173], v[172:173], v[180:181]
	v_pk_add_f32 v[176:177], v[176:177], v[182:183]
	s_nop 0
	v_pk_add_f32 v[172:173], v[172:173], v[176:177]
	s_nop 0
	v_add_f32_e32 v157, v172, v173
	v_fmamk_f32 v157, v157, 0x3a000000, v164
	v_rsq_f32_e32 v172, v157
	v_max_f32_e32 v157, v186, v186
	v_max_f32_e32 v19, v157, v19
	v_max3_f32 v157, v184, v185, v19
	v_mul_f32_e32 v172, 0x3d8293ee, v172
	v_pk_mul_f32 v[156:157], v[156:157], v[172:173] op_sel_hi:[1,0]
	s_nop 0
	v_fma_f32 v19, v28, v172, -v157
	v_fma_f32 v28, v29, v172, -v157
	v_fma_f32 v29, v30, v172, -v157
	v_fma_f32 v30, v31, v172, -v157
	v_fma_f32 v31, v24, v172, -v157
	v_fma_f32 v173, v25, v172, -v157
	v_fma_f32 v176, v26, v172, -v157
	v_fma_f32 v177, v27, v172, -v157
	v_exp_f32_e32 v24, v19
	v_exp_f32_e32 v25, v28
	v_exp_f32_e32 v28, v29
	v_exp_f32_e32 v29, v30
	v_fma_f32 v20, v20, v172, -v157
	v_fma_f32 v21, v21, v172, -v157
	v_fma_f32 v22, v22, v172, -v157
	v_fma_f32 v23, v23, v172, -v157
	v_fma_f32 v178, v16, v172, -v157
	v_fma_f32 v179, v17, v172, -v157
	v_fma_f32 v172, v18, v172, -v157
	v_sub_f32_e32 v180, v156, v157
	v_exp_f32_e32 v26, v31
	v_exp_f32_e32 v27, v173
	v_exp_f32_e32 v156, v176
	v_exp_f32_e32 v157, v177
	v_exp_f32_e32 v16, v20
	v_exp_f32_e32 v17, v21
	v_exp_f32_e32 v20, v22
	v_exp_f32_e32 v21, v23
	v_exp_f32_e32 v18, v178
	v_exp_f32_e32 v19, v179
	v_exp_f32_e32 v22, v172
	v_exp_f32_e32 v23, v180
	v_add_f32_e32 v30, v24, v25
	v_add_f32_e32 v31, v28, v29
	v_add_f32_e32 v172, v26, v27
	v_add_f32_e32 v173, v156, v157
	v_add_f32_e32 v30, v30, v31
	v_add_f32_e32 v176, v16, v17
	v_add_f32_e32 v177, v20, v21
	v_add_f32_e32 v31, v172, v173
	v_add_f32_e32 v30, 0, v30
	v_add_f32_e32 v178, v18, v19
	v_add_f32_e32 v179, v22, v23
	v_add_f32_e32 v172, v176, v177
	v_add_f32_e32 v30, v31, v30
	v_add_f32_e32 v30, v172, v30
	v_add_f32_e32 v31, v178, v179
	v_add_f32_e32 v30, v31, v30
	v_mov_b32_e32 v31, v30
	s_nop 1
	v_permlane16_swap_b32_e32 v30, v31
	s_waitcnt lgkmcnt(0)
	v_add_f32_e32 v30, v30, v31
	v_mov_b32_e32 v31, v30
	s_nop 1
	v_permlane32_swap_b32_e32 v30, v31
	s_and_saveexec_b64 s[46:47], vcc
	s_cbranch_execz .LBB0_629
	v_lshlrev_b32_e32 v172, 2, v171
	v_lshl_add_u32 v172, v172, 2, s63
	s_waitcnt lgkmcnt(0)
	v_add_f32_e32 v30, v30, v31
	ds_write_b32 v172, v30
.LBB0_629:
	s_or_b64 exec, exec, s[46:47]
	v_add_u32_e32 v172, 0xb0, v163
	v_add_u32_e32 v30, s39, v172
	s_waitcnt lgkmcnt(0)
	v_ashrrev_i32_e32 v31, 31, v30
	v_lshlrev_b64 v[176:177], 5, v[30:31]
	v_lshl_add_u64 v[180:181], s[22:23], 0, v[176:177]
	s_waitcnt vmcnt(0)
	v_mov_b32_e32 v176, v200
	v_mov_b32_e32 v177, v201
	v_mov_b32_e32 v178, v202
	v_mov_b32_e32 v179, v203
	v_mov_b32_e32 v180, v204
	v_mov_b32_e32 v181, v205
	v_mov_b32_e32 v182, v206
	v_mov_b32_e32 v183, v207
	v_lshl_add_u32 v173, v172, 4, 0
	v_add_u32_e32 v173, 0x20000, v173
	ds_read_b128 v[184:187], v173
	v_mov_b32_e32 v188, v3
	s_waitcnt lgkmcnt(0)
	v_max_f32_e32 v3, v187, v187
	v_mov_b32_e32 v190, v176
	v_mov_b32_e32 v191, v180
	v_mov_b32_e32 v180, v177
	v_mov_b32_e32 v176, v178
	v_mov_b32_e32 v177, v182
	v_mov_b32_e32 v182, v179
	v_pk_add_f32 v[178:179], v[190:191], v[180:181]
	v_pk_add_f32 v[176:177], v[176:177], v[182:183]
	s_nop 0
	v_pk_add_f32 v[176:177], v[178:179], v[176:177]
	s_nop 0
	v_add_f32_e32 v173, v176, v177
	v_fmamk_f32 v173, v173, 0x3a000000, v164
	v_rsq_f32_e32 v173, v173
	v_max_f32_e32 v176, v186, v186
	v_max_f32_e32 v3, v176, v3
	v_max3_f32 v189, v184, v185, v3
	v_mul_f32_e32 v176, 0x3d8293ee, v173
	v_pk_mul_f32 v[178:179], v[188:189], v[176:177] op_sel_hi:[1,0]
	s_nop 0
	v_fma_f32 v3, v12, v176, -v179
	v_fma_f32 v12, v13, v176, -v179
	v_fma_f32 v13, v14, v176, -v179
	v_fma_f32 v15, v15, v176, -v179
	v_fma_f32 v8, v8, v176, -v179
	v_fma_f32 v9, v9, v176, -v179
	v_fma_f32 v173, v10, v176, -v179
	v_fma_f32 v177, v11, v176, -v179
	v_exp_f32_e32 v10, v3
	v_exp_f32_e32 v11, v12
	v_exp_f32_e32 v14, v13
	v_exp_f32_e32 v15, v15
	v_fma_f32 v4, v4, v176, -v179
	v_fma_f32 v5, v5, v176, -v179
	v_fma_f32 v6, v6, v176, -v179
	v_fma_f32 v7, v7, v176, -v179
	v_exp_f32_e32 v8, v8
	v_exp_f32_e32 v9, v9
	v_exp_f32_e32 v12, v173
	v_exp_f32_e32 v13, v177
	v_fma_f32 v0, v0, v176, -v179
	v_fma_f32 v1, v1, v176, -v179
	v_fma_f32 v176, v2, v176, -v179
	v_sub_f32_e32 v178, v178, v179
	v_exp_f32_e32 v2, v4
	v_exp_f32_e32 v3, v5
	v_exp_f32_e32 v6, v6
	v_exp_f32_e32 v7, v7
	v_exp_f32_e32 v0, v0
	v_exp_f32_e32 v1, v1
	v_exp_f32_e32 v4, v176
	v_exp_f32_e32 v5, v178
	v_add_f32_e32 v173, v10, v11
	v_add_f32_e32 v176, v14, v15
	v_add_f32_e32 v177, v8, v9
	v_add_f32_e32 v178, v12, v13
	v_add_f32_e32 v173, v173, v176
	v_add_f32_e32 v179, v2, v3
	v_add_f32_e32 v180, v6, v7
	v_add_f32_e32 v176, v177, v178
	v_add_f32_e32 v173, 0, v173
	v_add_f32_e32 v181, v0, v1
	v_add_f32_e32 v182, v4, v5
	v_add_f32_e32 v177, v179, v180
	v_add_f32_e32 v173, v176, v173
	v_add_f32_e32 v173, v177, v173
	v_add_f32_e32 v176, v181, v182
	v_add_f32_e32 v173, v176, v173
	v_mov_b32_e32 v136, v173
	s_nop 1
	v_permlane16_swap_b32_e32 v173, v136
	s_waitcnt lgkmcnt(0)
	v_add_f32_e32 v136, v173, v136
	v_mov_b32_e32 v165, v136
	s_nop 1
	v_permlane32_swap_b32_e32 v136, v165
	s_and_saveexec_b64 s[46:47], vcc
	s_cbranch_execz .LBB0_631
	v_lshlrev_b32_e32 v173, 2, v172
	v_lshl_add_u32 v173, v173, 2, s63
	s_waitcnt lgkmcnt(0)
	v_add_f32_e32 v136, v136, v165
	ds_write_b32 v173, v136

.LBB0_710:
	v_lshl_or_b32 v164, s26, 8, v172
	s_lshl_b32 s41, s48, 8
	v_ashrrev_i32_e32 v165, 31, v164
	v_add_u32_e32 v166, s41, v170
	v_lshlrev_b64 v[202:203], 1, v[164:165]
	v_ashrrev_i32_e32 v167, 31, v166
	v_lshl_add_u64 v[168:169], s[28:29], 0, v[202:203]
	v_lshlrev_b64 v[204:205], 12, v[166:167]
	v_lshl_add_u64 v[128:129], v[168:169], 0, v[204:205]
	global_load_dwordx4 v[194:197], v[128:129], off
	global_load_dwordx4 v[198:201], v[128:129], off offset:256
	v_or_b32_e32 v128, 16, v166
	v_or_b32_e32 v130, 32, v166
	v_or_b32_e32 v132, 48, v166
	v_ashrrev_i32_e32 v129, 31, v128
	v_ashrrev_i32_e32 v131, 31, v130
	v_ashrrev_i32_e32 v133, 31, v132
	v_lshlrev_b64 v[128:129], 12, v[128:129]
	v_lshlrev_b64 v[130:131], 12, v[130:131]
	v_lshlrev_b64 v[132:133], 12, v[132:133]
	v_lshl_add_u64 v[128:129], v[168:169], 0, v[128:129]
	v_lshl_add_u64 v[130:131], v[168:169], 0, v[130:131]
	v_lshl_add_u64 v[192:193], v[168:169], 0, v[132:133]
	global_load_dwordx4 v[148:151], v[128:129], off
	global_load_dwordx4 v[144:147], v[128:129], off offset:256
	global_load_dwordx4 v[140:143], v[130:131], off
	global_load_dwordx4 v[136:139], v[130:131], off offset:256
	global_load_dwordx4 v[132:135], v[192:193], off
	s_nop 0
	global_load_dwordx4 v[128:131], v[192:193], off offset:256
	v_and_b32_e32 v192, 64, v191
	v_xor_b32_e32 v167, 16, v191
	v_add_u32_e32 v192, 64, v192
	v_xor_b32_e32 v193, 32, v191
	v_cmp_lt_i32_e32 vcc, v167, v192
	s_waitcnt vmcnt(0)
	v_lshlrev_b32_e32 v206, 16, v194
	v_cndmask_b32_e32 v167, v191, v167, vcc
	v_cmp_lt_i32_e32 vcc, v193, v192
	v_and_b32_e32 v207, 0xffff0000, v194
	v_lshlrev_b32_e32 v194, 16, v195
	v_and_b32_e32 v195, 0xffff0000, v195
	v_lshlrev_b32_e32 v208, 16, v196
	v_and_b32_e32 v209, 0xffff0000, v196
	v_lshlrev_b32_e32 v196, 16, v197
	v_and_b32_e32 v197, 0xffff0000, v197
	v_lshlrev_b32_e32 v210, 16, v198
	v_and_b32_e32 v211, 0xffff0000, v198
	v_lshlrev_b32_e32 v198, 16, v199
	v_and_b32_e32 v199, 0xffff0000, v199
	v_lshlrev_b32_e32 v212, 16, v200
	v_and_b32_e32 v213, 0xffff0000, v200
	v_lshlrev_b32_e32 v200, 16, v201
	v_and_b32_e32 v201, 0xffff0000, v201
	v_cndmask_b32_e32 v193, v191, v193, vcc
	v_pk_add_f32 v[126:127], v[126:127], v[194:195]
	v_pk_add_f32 v[124:125], v[124:125], v[206:207]
	v_pk_add_f32 v[122:123], v[122:123], v[196:197]
	v_pk_add_f32 v[120:121], v[120:121], v[208:209]
	v_pk_add_f32 v[118:119], v[118:119], v[198:199]
	v_pk_add_f32 v[116:117], v[116:117], v[210:211]
	v_pk_add_f32 v[194:195], v[114:115], v[200:201]
	v_pk_add_f32 v[196:197], v[112:113], v[212:213]
	v_lshlrev_b32_e32 v192, 2, v167
	v_lshlrev_b32_e32 v167, 2, v193
	v_cvt_pk_bf16_f32 v112, v124, v125
	v_cvt_pk_bf16_f32 v113, v126, v127
	v_cvt_pk_bf16_f32 v114, v120, v121
	v_cvt_pk_bf16_f32 v115, v122, v123
	v_mul_f32_e32 v125, v125, v125
	v_mul_f32_e32 v127, v127, v127
	v_mul_f32_e32 v121, v121, v121
	v_mul_f32_e32 v123, v123, v123
	v_mul_f32_e32 v193, v117, v117
	v_mul_f32_e32 v198, v119, v119
	v_mul_f32_e32 v199, v197, v197
	v_mul_f32_e32 v200, v195, v195
	v_fmac_f32_e32 v125, v124, v124
	v_fmac_f32_e32 v127, v126, v126
	v_fmac_f32_e32 v121, v120, v120
	v_fmac_f32_e32 v123, v122, v122
	v_fmac_f32_e32 v193, v116, v116
	v_fmac_f32_e32 v198, v118, v118
	v_fmac_f32_e32 v199, v196, v196
	v_fmac_f32_e32 v200, v194, v194
	v_add_f32_e32 v120, v125, v127
	v_add_f32_e32 v121, v121, v123
	v_add_f32_e32 v122, v193, v198
	v_add_f32_e32 v123, v199, v200
	v_add_f32_e32 v120, v120, v121
	v_add_f32_e32 v121, v122, v123
	v_add_f32_e32 v122, v120, v121
	v_mov_b32_e32 v123, v122
	s_nop 1
	v_permlane16_swap_b32_e32 v122, v123
	v_lshl_add_u64 v[120:121], s[28:29], 0, v[204:205]
	v_lshl_add_u64 v[120:121], v[120:121], 0, v[202:203]
	global_store_dwordx4 v[120:121], v[112:115], off
	s_waitcnt lgkmcnt(0)
	s_nop 0
	v_add_f32_e32 v112, v122, v123
	v_mov_b32_e32 v113, v112
	s_nop 1
	v_permlane32_swap_b32_e32 v112, v113
	v_cvt_pk_bf16_f32 v114, v116, v117
	v_cvt_pk_bf16_f32 v115, v118, v119
	v_cvt_pk_bf16_f32 v116, v196, v197
	v_cvt_pk_bf16_f32 v117, v194, v195
	global_store_dwordx4 v[120:121], v[114:117], off offset:256
	s_and_saveexec_b64 s[48:49], s[6:7]
	s_cbranch_execz .LBB0_712
	s_waitcnt lgkmcnt(0)
	v_add_f32_e32 v112, v112, v113
	ds_write_b32 v183, v112
.LBB0_712:
	s_or_b64 exec, exec, s[48:49]
	v_lshlrev_b32_e32 v114, 16, v148
	v_and_b32_e32 v115, 0xffff0000, v148
	v_lshlrev_b32_e32 v116, 16, v149
	v_and_b32_e32 v117, 0xffff0000, v149
	v_lshlrev_b32_e32 v118, 16, v150
	v_and_b32_e32 v119, 0xffff0000, v150
	v_pk_add_f32 v[108:109], v[108:109], v[114:115]
	v_pk_add_f32 v[110:111], v[110:111], v[116:117]
	v_pk_add_f32 v[116:117], v[104:105], v[118:119]
	v_cvt_pk_bf16_f32 v104, v108, v109
	v_mul_f32_e32 v109, v109, v109
	v_lshlrev_b32_e32 v120, 16, v151
	v_and_b32_e32 v121, 0xffff0000, v151
	v_fmac_f32_e32 v109, v108, v108
	v_mul_f32_e32 v108, v111, v111
	v_pk_add_f32 v[114:115], v[106:107], v[120:121]
	v_fmac_f32_e32 v108, v110, v110
	v_cvt_pk_bf16_f32 v105, v110, v111
	v_add_f32_e32 v108, v109, v108
	v_mul_f32_e32 v109, v117, v117
	v_mul_f32_e32 v110, v115, v115
	v_fmac_f32_e32 v109, v116, v116
	v_fmac_f32_e32 v110, v114, v114
	v_add_f32_e32 v109, v109, v110
	v_add_f32_e32 v118, v108, v109
	v_lshlrev_b32_e32 v108, 16, v144
	v_and_b32_e32 v109, 0xffff0000, v144
	v_lshlrev_b32_e32 v110, 16, v145
	v_and_b32_e32 v111, 0xffff0000, v145
	v_cvt_pk_bf16_f32 v107, v114, v115
	v_lshlrev_b32_e32 v114, 16, v146
	v_and_b32_e32 v115, 0xffff0000, v146
	v_pk_add_f32 v[102:103], v[102:103], v[110:111]
	v_pk_add_f32 v[100:101], v[100:101], v[108:109]
	v_cvt_pk_bf16_f32 v106, v116, v117
	v_lshlrev_b32_e32 v116, 16, v147
	v_and_b32_e32 v117, 0xffff0000, v147
	v_pk_add_f32 v[110:111], v[96:97], v[114:115]
	v_mul_f32_e32 v96, v101, v101
	v_mul_f32_e32 v97, v103, v103
	v_pk_add_f32 v[108:109], v[98:99], v[116:117]
	v_fmac_f32_e32 v96, v100, v100
	v_fmac_f32_e32 v97, v102, v102
	v_add_f32_e32 v96, v96, v97
	v_mul_f32_e32 v97, v111, v111
	v_mul_f32_e32 v98, v109, v109
	v_fmac_f32_e32 v97, v110, v110
	v_fmac_f32_e32 v98, v108, v108
	v_add_f32_e32 v97, v97, v98
	v_add_f32_e32 v96, v96, v97
	v_add_f32_e32 v99, v118, v96
	v_mov_b32_e32 v114, v99
	s_nop 1
	v_permlane16_swap_b32_e32 v99, v114
	v_add_u32_e32 v112, s41, v173
	s_waitcnt lgkmcnt(1)
	v_ashrrev_i32_e32 v113, 31, v112
	v_lshlrev_b64 v[112:113], 12, v[112:113]
	v_lshl_add_u64 v[96:97], s[28:29], 0, v[112:113]
	v_lshl_add_u64 v[112:113], v[164:165], 1, v[96:97]
	s_waitcnt lgkmcnt(0)
	v_add_f32_e32 v96, v99, v114
	v_mov_b32_e32 v97, v96
	s_nop 1
	v_permlane32_swap_b32_e32 v96, v97
	v_cvt_pk_bf16_f32 v98, v100, v101
	v_cvt_pk_bf16_f32 v99, v102, v103
	v_cvt_pk_bf16_f32 v100, v110, v111
	v_cvt_pk_bf16_f32 v101, v108, v109
	global_store_dwordx4 v[112:113], v[104:107], off
	global_store_dwordx4 v[112:113], v[98:101], off offset:256
	s_and_saveexec_b64 s[48:49], s[6:7]
	s_cbranch_execz .LBB0_714
	s_waitcnt lgkmcnt(0)
	v_add_f32_e32 v96, v96, v97
	ds_write_b32 v184, v96
.LBB0_714:
	s_or_b64 exec, exec, s[48:49]
	v_lshlrev_b32_e32 v98, 16, v140
	v_and_b32_e32 v99, 0xffff0000, v140
	v_lshlrev_b32_e32 v100, 16, v141
	v_and_b32_e32 v101, 0xffff0000, v141
	v_lshlrev_b32_e32 v102, 16, v142
	v_and_b32_e32 v103, 0xffff0000, v142
	v_pk_add_f32 v[92:93], v[92:93], v[98:99]
	v_pk_add_f32 v[94:95], v[94:95], v[100:101]
	v_pk_add_f32 v[100:101], v[88:89], v[102:103]
	v_cvt_pk_bf16_f32 v88, v92, v93
	v_mul_f32_e32 v93, v93, v93
	v_lshlrev_b32_e32 v104, 16, v143
	v_and_b32_e32 v105, 0xffff0000, v143
	v_fmac_f32_e32 v93, v92, v92
	v_mul_f32_e32 v92, v95, v95
	v_pk_add_f32 v[98:99], v[90:91], v[104:105]
	v_fmac_f32_e32 v92, v94, v94
	v_cvt_pk_bf16_f32 v89, v94, v95
	v_add_f32_e32 v92, v93, v92
	v_mul_f32_e32 v93, v101, v101
	v_mul_f32_e32 v94, v99, v99
	v_fmac_f32_e32 v93, v100, v100
	v_fmac_f32_e32 v94, v98, v98
	v_add_f32_e32 v93, v93, v94
	v_add_f32_e32 v102, v92, v93
	v_lshlrev_b32_e32 v92, 16, v136
	v_and_b32_e32 v93, 0xffff0000, v136
	v_lshlrev_b32_e32 v94, 16, v137
	v_and_b32_e32 v95, 0xffff0000, v137
	v_cvt_pk_bf16_f32 v91, v98, v99
	v_lshlrev_b32_e32 v98, 16, v138
	v_and_b32_e32 v99, 0xffff0000, v138
	v_pk_add_f32 v[86:87], v[86:87], v[94:95]
	v_pk_add_f32 v[84:85], v[84:85], v[92:93]
	v_cvt_pk_bf16_f32 v90, v100, v101
	v_lshlrev_b32_e32 v100, 16, v139
	v_and_b32_e32 v101, 0xffff0000, v139
	v_pk_add_f32 v[94:95], v[80:81], v[98:99]
	v_mul_f32_e32 v80, v85, v85
	v_mul_f32_e32 v81, v87, v87
	v_pk_add_f32 v[92:93], v[82:83], v[100:101]
	v_fmac_f32_e32 v80, v84, v84
	v_fmac_f32_e32 v81, v86, v86
	v_add_f32_e32 v80, v80, v81
	v_mul_f32_e32 v81, v95, v95
	v_mul_f32_e32 v82, v93, v93
	v_fmac_f32_e32 v81, v94, v94
	v_fmac_f32_e32 v82, v92, v92
	v_add_f32_e32 v81, v81, v82
	v_add_f32_e32 v80, v80, v81
	v_add_f32_e32 v83, v102, v80
	v_mov_b32_e32 v98, v83
	s_nop 1
	v_permlane16_swap_b32_e32 v83, v98
	v_add_u32_e32 v96, s41, v176
	s_waitcnt lgkmcnt(1)
	v_ashrrev_i32_e32 v97, 31, v96
	v_lshlrev_b64 v[96:97], 12, v[96:97]
	v_lshl_add_u64 v[80:81], s[28:29], 0, v[96:97]
	v_lshl_add_u64 v[96:97], v[164:165], 1, v[80:81]
	s_waitcnt lgkmcnt(0)
	v_add_f32_e32 v80, v83, v98
	v_mov_b32_e32 v81, v80
	s_nop 1
	v_permlane32_swap_b32_e32 v80, v81
	v_cvt_pk_bf16_f32 v82, v84, v85
	v_cvt_pk_bf16_f32 v83, v86, v87
	v_cvt_pk_bf16_f32 v84, v94, v95
	v_cvt_pk_bf16_f32 v85, v92, v93
	global_store_dwordx4 v[96:97], v[88:91], off
	global_store_dwordx4 v[96:97], v[82:85], off offset:256
	s_and_saveexec_b64 s[48:49], s[6:7]
	s_cbranch_execz .LBB0_716
	s_waitcnt lgkmcnt(0)
	v_add_f32_e32 v80, v80, v81
	ds_write_b32 v185, v80
.LBB0_716:
	s_or_b64 exec, exec, s[48:49]
	v_lshlrev_b32_e32 v82, 16, v132
	v_and_b32_e32 v83, 0xffff0000, v132
	v_lshlrev_b32_e32 v84, 16, v133
	v_and_b32_e32 v85, 0xffff0000, v133
	v_lshlrev_b32_e32 v86, 16, v134
	v_and_b32_e32 v87, 0xffff0000, v134
	v_pk_add_f32 v[76:77], v[76:77], v[82:83]
	v_pk_add_f32 v[78:79], v[78:79], v[84:85]
	v_pk_add_f32 v[84:85], v[72:73], v[86:87]
	v_cvt_pk_bf16_f32 v72, v76, v77
	v_mul_f32_e32 v77, v77, v77
	v_lshlrev_b32_e32 v88, 16, v135
	v_and_b32_e32 v89, 0xffff0000, v135
	v_fmac_f32_e32 v77, v76, v76
	v_mul_f32_e32 v76, v79, v79
	v_pk_add_f32 v[82:83], v[74:75], v[88:89]
	v_fmac_f32_e32 v76, v78, v78
	v_cvt_pk_bf16_f32 v73, v78, v79
	v_add_f32_e32 v76, v77, v76
	v_mul_f32_e32 v77, v85, v85
	v_mul_f32_e32 v78, v83, v83
	v_fmac_f32_e32 v77, v84, v84
	v_fmac_f32_e32 v78, v82, v82
	v_add_f32_e32 v77, v77, v78
	v_add_f32_e32 v86, v76, v77
	v_lshlrev_b32_e32 v76, 16, v128
	v_and_b32_e32 v77, 0xffff0000, v128
	v_lshlrev_b32_e32 v78, 16, v129
	v_and_b32_e32 v79, 0xffff0000, v129
	v_cvt_pk_bf16_f32 v75, v82, v83
	v_lshlrev_b32_e32 v82, 16, v130
	v_and_b32_e32 v83, 0xffff0000, v130
	v_pk_add_f32 v[70:71], v[70:71], v[78:79]
	v_pk_add_f32 v[68:69], v[68:69], v[76:77]
	v_cvt_pk_bf16_f32 v74, v84, v85
	v_lshlrev_b32_e32 v84, 16, v131
	v_and_b32_e32 v85, 0xffff0000, v131
	v_pk_add_f32 v[78:79], v[64:65], v[82:83]
	v_mul_f32_e32 v64, v69, v69
	v_mul_f32_e32 v65, v71, v71
	v_pk_add_f32 v[76:77], v[66:67], v[84:85]
	v_fmac_f32_e32 v64, v68, v68
	v_fmac_f32_e32 v65, v70, v70
	v_add_f32_e32 v64, v64, v65
	v_mul_f32_e32 v65, v79, v79
	v_mul_f32_e32 v66, v77, v77
	v_fmac_f32_e32 v65, v78, v78
	v_fmac_f32_e32 v66, v76, v76
	v_add_f32_e32 v65, v65, v66
	v_add_f32_e32 v64, v64, v65
	v_add_f32_e32 v67, v86, v64
	v_mov_b32_e32 v82, v67
	s_nop 1
	v_permlane16_swap_b32_e32 v67, v82
	v_add_u32_e32 v80, s41, v177
	s_waitcnt lgkmcnt(1)
	v_ashrrev_i32_e32 v81, 31, v80
	v_lshlrev_b64 v[80:81], 12, v[80:81]
	v_lshl_add_u64 v[64:65], s[28:29], 0, v[80:81]
	v_lshl_add_u64 v[80:81], v[164:165], 1, v[64:65]
	s_waitcnt lgkmcnt(0)
	v_add_f32_e32 v64, v67, v82
	v_mov_b32_e32 v65, v64
	s_nop 1
	v_permlane32_swap_b32_e32 v64, v65
	v_cvt_pk_bf16_f32 v66, v68, v69
	v_cvt_pk_bf16_f32 v67, v70, v71
	v_cvt_pk_bf16_f32 v68, v78, v79
	v_cvt_pk_bf16_f32 v69, v76, v77
	global_store_dwordx4 v[80:81], v[72:75], off
	global_store_dwordx4 v[80:81], v[66:69], off offset:256
	s_and_saveexec_b64 s[48:49], s[6:7]
	s_cbranch_execz .LBB0_718
	s_waitcnt lgkmcnt(0)
	v_add_f32_e32 v64, v64, v65
	ds_write_b32 v186, v64
.LBB0_718:
	s_or_b64 exec, exec, s[48:49]
	v_add_u32_e32 v64, s41, v178
	s_waitcnt lgkmcnt(0)
	v_ashrrev_i32_e32 v65, 31, v64
	v_lshlrev_b64 v[96:97], 12, v[64:65]
	v_lshl_add_u64 v[66:67], v[168:169], 0, v[96:97]
	global_load_dwordx4 v[88:91], v[66:67], off
	global_load_dwordx4 v[92:95], v[66:67], off offset:256
	v_or_b32_e32 v66, 16, v64
	v_or_b32_e32 v68, 32, v64
	v_or_b32_e32 v64, 48, v64
	v_ashrrev_i32_e32 v67, 31, v66
	v_ashrrev_i32_e32 v69, 31, v68
	v_ashrrev_i32_e32 v65, 31, v64
	v_lshlrev_b64 v[66:67], 12, v[66:67]
	v_lshlrev_b64 v[68:69], 12, v[68:69]
	v_lshlrev_b64 v[64:65], 12, v[64:65]
	v_lshl_add_u64 v[66:67], v[168:169], 0, v[66:67]
	v_lshl_add_u64 v[68:69], v[168:169], 0, v[68:69]
	v_lshl_add_u64 v[64:65], v[168:169], 0, v[64:65]
	global_load_dwordx4 v[84:87], v[66:67], off
	global_load_dwordx4 v[80:83], v[66:67], off offset:256
	global_load_dwordx4 v[76:79], v[68:69], off
	global_load_dwordx4 v[72:75], v[68:69], off offset:256
	s_nop 0
	global_load_dwordx4 v[68:71], v[64:65], off
	s_nop 0
	global_load_dwordx4 v[64:67], v[64:65], off offset:256
	s_waitcnt vmcnt(7)
	v_lshlrev_b32_e32 v98, 16, v88
	v_and_b32_e32 v99, 0xffff0000, v88
	v_lshlrev_b32_e32 v88, 16, v89
	v_and_b32_e32 v89, 0xffff0000, v89
	v_lshlrev_b32_e32 v100, 16, v90
	v_and_b32_e32 v101, 0xffff0000, v90
	v_lshlrev_b32_e32 v90, 16, v91
	v_and_b32_e32 v91, 0xffff0000, v91
	s_waitcnt vmcnt(6)
	v_lshlrev_b32_e32 v102, 16, v92
	v_and_b32_e32 v103, 0xffff0000, v92
	v_lshlrev_b32_e32 v92, 16, v93
	v_and_b32_e32 v93, 0xffff0000, v93
	v_lshlrev_b32_e32 v104, 16, v94
	v_and_b32_e32 v105, 0xffff0000, v94
	v_lshlrev_b32_e32 v94, 16, v95
	v_and_b32_e32 v95, 0xffff0000, v95
	v_pk_add_f32 v[62:63], v[62:63], v[88:89]
	v_pk_add_f32 v[60:61], v[60:61], v[98:99]
	v_pk_add_f32 v[58:59], v[58:59], v[90:91]
	v_pk_add_f32 v[56:57], v[56:57], v[100:101]
	v_pk_add_f32 v[54:55], v[54:55], v[92:93]
	v_pk_add_f32 v[52:53], v[52:53], v[102:103]
	v_pk_add_f32 v[88:89], v[50:51], v[94:95]
	v_pk_add_f32 v[90:91], v[48:49], v[104:105]
	v_cvt_pk_bf16_f32 v48, v60, v61
	v_cvt_pk_bf16_f32 v49, v62, v63
	v_cvt_pk_bf16_f32 v50, v56, v57
	v_cvt_pk_bf16_f32 v51, v58, v59
	v_mul_f32_e32 v61, v61, v61
	v_mul_f32_e32 v63, v63, v63
	v_mul_f32_e32 v57, v57, v57
	v_mul_f32_e32 v59, v59, v59
	v_mul_f32_e32 v92, v53, v53
	v_mul_f32_e32 v93, v55, v55
	v_mul_f32_e32 v94, v91, v91
	v_mul_f32_e32 v95, v89, v89
	v_fmac_f32_e32 v61, v60, v60
	v_fmac_f32_e32 v63, v62, v62
	v_fmac_f32_e32 v57, v56, v56
	v_fmac_f32_e32 v59, v58, v58
	v_fmac_f32_e32 v92, v52, v52
	v_fmac_f32_e32 v93, v54, v54
	v_fmac_f32_e32 v94, v90, v90
	v_fmac_f32_e32 v95, v88, v88
	v_add_f32_e32 v56, v61, v63
	v_add_f32_e32 v57, v57, v59
	v_add_f32_e32 v58, v92, v93
	v_add_f32_e32 v59, v94, v95
	v_add_f32_e32 v56, v56, v57
	v_add_f32_e32 v57, v58, v59
	v_add_f32_e32 v58, v56, v57
	v_mov_b32_e32 v59, v58
	s_nop 1
	v_permlane16_swap_b32_e32 v58, v59
	v_lshl_add_u64 v[56:57], s[28:29], 0, v[96:97]
	v_lshl_add_u64 v[56:57], v[164:165], 1, v[56:57]
	global_store_dwordx4 v[56:57], v[48:51], off
	s_waitcnt lgkmcnt(0)
	s_nop 0
	v_add_f32_e32 v48, v58, v59
	v_mov_b32_e32 v49, v48
	s_nop 1
	v_permlane32_swap_b32_e32 v48, v49
	v_cvt_pk_bf16_f32 v50, v52, v53
	v_cvt_pk_bf16_f32 v51, v54, v55
	v_cvt_pk_bf16_f32 v52, v90, v91
	v_cvt_pk_bf16_f32 v53, v88, v89
	global_store_dwordx4 v[56:57], v[50:53], off offset:256
	s_and_saveexec_b64 s[48:49], s[6:7]
	s_cbranch_execz .LBB0_720
	s_waitcnt lgkmcnt(0)
	v_add_f32_e32 v48, v48, v49
	ds_write_b32 v187, v48
.LBB0_720:
	s_or_b64 exec, exec, s[48:49]
	s_waitcnt vmcnt(7)
	v_lshlrev_b32_e32 v50, 16, v84
	v_and_b32_e32 v51, 0xffff0000, v84
	v_lshlrev_b32_e32 v52, 16, v85
	v_and_b32_e32 v53, 0xffff0000, v85
	v_lshlrev_b32_e32 v54, 16, v86
	v_and_b32_e32 v55, 0xffff0000, v86
	v_pk_add_f32 v[44:45], v[44:45], v[50:51]
	v_pk_add_f32 v[46:47], v[46:47], v[52:53]
	v_pk_add_f32 v[52:53], v[40:41], v[54:55]
	v_cvt_pk_bf16_f32 v40, v44, v45
	v_mul_f32_e32 v45, v45, v45
	v_lshlrev_b32_e32 v56, 16, v87
	v_and_b32_e32 v57, 0xffff0000, v87
	v_fmac_f32_e32 v45, v44, v44
	v_mul_f32_e32 v44, v47, v47
	v_pk_add_f32 v[50:51], v[42:43], v[56:57]
	v_fmac_f32_e32 v44, v46, v46
	v_cvt_pk_bf16_f32 v41, v46, v47
	v_add_f32_e32 v44, v45, v44
	v_mul_f32_e32 v45, v53, v53
	v_mul_f32_e32 v46, v51, v51
	v_fmac_f32_e32 v45, v52, v52
	v_fmac_f32_e32 v46, v50, v50
	v_add_f32_e32 v45, v45, v46
	v_add_f32_e32 v54, v44, v45
	s_waitcnt vmcnt(6)
	v_lshlrev_b32_e32 v44, 16, v80
	v_and_b32_e32 v45, 0xffff0000, v80
	v_lshlrev_b32_e32 v46, 16, v81
	v_and_b32_e32 v47, 0xffff0000, v81
	v_cvt_pk_bf16_f32 v43, v50, v51
	v_lshlrev_b32_e32 v50, 16, v82
	v_and_b32_e32 v51, 0xffff0000, v82
	v_pk_add_f32 v[38:39], v[38:39], v[46:47]
	v_pk_add_f32 v[36:37], v[36:37], v[44:45]
	v_cvt_pk_bf16_f32 v42, v52, v53
	v_lshlrev_b32_e32 v52, 16, v83
	v_and_b32_e32 v53, 0xffff0000, v83
	v_pk_add_f32 v[46:47], v[32:33], v[50:51]
	v_mul_f32_e32 v32, v37, v37
	v_mul_f32_e32 v33, v39, v39
	v_pk_add_f32 v[44:45], v[34:35], v[52:53]
	v_fmac_f32_e32 v32, v36, v36
	v_fmac_f32_e32 v33, v38, v38
	v_add_f32_e32 v32, v32, v33
	v_mul_f32_e32 v33, v47, v47
	v_mul_f32_e32 v34, v45, v45
	v_fmac_f32_e32 v33, v46, v46
	v_fmac_f32_e32 v34, v44, v44
	v_add_f32_e32 v33, v33, v34
	v_add_f32_e32 v32, v32, v33
	v_add_f32_e32 v35, v54, v32
	v_mov_b32_e32 v50, v35
	s_nop 1
	v_permlane16_swap_b32_e32 v35, v50
	v_add_u32_e32 v48, 0x90, v166
	s_waitcnt lgkmcnt(1)
	v_ashrrev_i32_e32 v49, 31, v48
	v_lshlrev_b64 v[48:49], 12, v[48:49]
	v_lshl_add_u64 v[32:33], s[28:29], 0, v[48:49]
	v_lshl_add_u64 v[48:49], v[164:165], 1, v[32:33]
	s_waitcnt lgkmcnt(0)
	v_add_f32_e32 v32, v35, v50
	v_mov_b32_e32 v33, v32
	s_nop 1
	v_permlane32_swap_b32_e32 v32, v33
	v_cvt_pk_bf16_f32 v34, v36, v37
	v_cvt_pk_bf16_f32 v35, v38, v39
	v_cvt_pk_bf16_f32 v36, v46, v47
	v_cvt_pk_bf16_f32 v37, v44, v45
	global_store_dwordx4 v[48:49], v[40:43], off
	global_store_dwordx4 v[48:49], v[34:37], off offset:256
	s_and_saveexec_b64 s[48:49], s[6:7]
	s_cbranch_execz .LBB0_722
	s_waitcnt lgkmcnt(0)
	v_add_f32_e32 v32, v32, v33
	ds_write_b32 v183, v32 offset:2304
.LBB0_722:
	s_or_b64 exec, exec, s[48:49]
	s_waitcnt vmcnt(7)
	v_lshlrev_b32_e32 v34, 16, v76
	v_and_b32_e32 v35, 0xffff0000, v76
	v_lshlrev_b32_e32 v36, 16, v77
	v_and_b32_e32 v37, 0xffff0000, v77
	v_lshlrev_b32_e32 v38, 16, v78
	v_and_b32_e32 v39, 0xffff0000, v78
	v_pk_add_f32 v[28:29], v[28:29], v[34:35]
	v_pk_add_f32 v[30:31], v[30:31], v[36:37]
	v_pk_add_f32 v[36:37], v[24:25], v[38:39]
	v_cvt_pk_bf16_f32 v24, v28, v29
	v_mul_f32_e32 v29, v29, v29
	v_lshlrev_b32_e32 v40, 16, v79
	v_and_b32_e32 v41, 0xffff0000, v79
	v_fmac_f32_e32 v29, v28, v28
	v_mul_f32_e32 v28, v31, v31
	v_pk_add_f32 v[34:35], v[26:27], v[40:41]
	v_fmac_f32_e32 v28, v30, v30
	v_cvt_pk_bf16_f32 v25, v30, v31
	v_add_f32_e32 v28, v29, v28
	v_mul_f32_e32 v29, v37, v37
	v_mul_f32_e32 v30, v35, v35
	v_fmac_f32_e32 v29, v36, v36
	v_fmac_f32_e32 v30, v34, v34
	v_add_f32_e32 v29, v29, v30
	v_add_f32_e32 v38, v28, v29
	s_waitcnt vmcnt(6)
	v_lshlrev_b32_e32 v28, 16, v72
	v_and_b32_e32 v29, 0xffff0000, v72
	v_lshlrev_b32_e32 v30, 16, v73
	v_and_b32_e32 v31, 0xffff0000, v73
	v_cvt_pk_bf16_f32 v27, v34, v35
	v_lshlrev_b32_e32 v34, 16, v74
	v_and_b32_e32 v35, 0xffff0000, v74
	v_pk_add_f32 v[22:23], v[22:23], v[30:31]
	v_pk_add_f32 v[20:21], v[20:21], v[28:29]
	v_cvt_pk_bf16_f32 v26, v36, v37
	v_lshlrev_b32_e32 v36, 16, v75
	v_and_b32_e32 v37, 0xffff0000, v75
	v_pk_add_f32 v[30:31], v[16:17], v[34:35]
	v_mul_f32_e32 v16, v21, v21
	v_mul_f32_e32 v17, v23, v23
	v_pk_add_f32 v[28:29], v[18:19], v[36:37]
	v_fmac_f32_e32 v16, v20, v20
	v_fmac_f32_e32 v17, v22, v22
	v_add_f32_e32 v16, v16, v17
	v_mul_f32_e32 v17, v31, v31
	v_mul_f32_e32 v18, v29, v29
	v_fmac_f32_e32 v17, v30, v30
	v_fmac_f32_e32 v18, v28, v28
	v_add_f32_e32 v17, v17, v18
	v_add_f32_e32 v16, v16, v17
	v_add_f32_e32 v19, v38, v16
	v_mov_b32_e32 v34, v19
	s_nop 1
	v_permlane16_swap_b32_e32 v19, v34
	v_add_u32_e32 v32, 0xa0, v166
	s_waitcnt lgkmcnt(1)
	v_ashrrev_i32_e32 v33, 31, v32
	v_lshlrev_b64 v[32:33], 12, v[32:33]
	v_lshl_add_u64 v[16:17], s[28:29], 0, v[32:33]
	v_lshl_add_u64 v[32:33], v[164:165], 1, v[16:17]
	s_waitcnt lgkmcnt(0)
	v_add_f32_e32 v16, v19, v34
	v_mov_b32_e32 v17, v16
	s_nop 1
	v_permlane32_swap_b32_e32 v16, v17
	v_cvt_pk_bf16_f32 v18, v20, v21
	v_cvt_pk_bf16_f32 v19, v22, v23
	v_cvt_pk_bf16_f32 v20, v30, v31
	v_cvt_pk_bf16_f32 v21, v28, v29
	global_store_dwordx4 v[32:33], v[24:27], off
	global_store_dwordx4 v[32:33], v[18:21], off offset:256
	s_and_saveexec_b64 s[48:49], s[6:7]
	s_cbranch_execz .LBB0_724
	s_waitcnt lgkmcnt(0)
	v_add_f32_e32 v16, v16, v17
	ds_write_b32 v183, v16 offset:2560
.LBB0_724:
	s_or_b64 exec, exec, s[48:49]
	s_waitcnt vmcnt(7)
	v_lshlrev_b32_e32 v18, 16, v68
	v_and_b32_e32 v19, 0xffff0000, v68
	v_lshlrev_b32_e32 v20, 16, v69
	v_and_b32_e32 v21, 0xffff0000, v69
	v_lshlrev_b32_e32 v22, 16, v70
	v_and_b32_e32 v23, 0xffff0000, v70
	v_pk_add_f32 v[12:13], v[12:13], v[18:19]
	v_pk_add_f32 v[14:15], v[14:15], v[20:21]
	v_pk_add_f32 v[20:21], v[8:9], v[22:23]
	v_cvt_pk_bf16_f32 v8, v12, v13
	v_mul_f32_e32 v13, v13, v13
	v_lshlrev_b32_e32 v24, 16, v71
	v_and_b32_e32 v25, 0xffff0000, v71
	v_fmac_f32_e32 v13, v12, v12
	v_mul_f32_e32 v12, v15, v15
	v_pk_add_f32 v[18:19], v[10:11], v[24:25]
	v_fmac_f32_e32 v12, v14, v14
	v_cvt_pk_bf16_f32 v9, v14, v15
	v_add_f32_e32 v12, v13, v12
	v_mul_f32_e32 v13, v21, v21
	v_mul_f32_e32 v14, v19, v19
	v_fmac_f32_e32 v13, v20, v20
	v_fmac_f32_e32 v14, v18, v18
	v_add_f32_e32 v13, v13, v14
	v_add_f32_e32 v22, v12, v13
	s_waitcnt vmcnt(6)
	v_lshlrev_b32_e32 v12, 16, v64
	v_and_b32_e32 v13, 0xffff0000, v64
	v_lshlrev_b32_e32 v14, 16, v65
	v_and_b32_e32 v15, 0xffff0000, v65
	v_cvt_pk_bf16_f32 v11, v18, v19
	v_lshlrev_b32_e32 v18, 16, v66
	v_and_b32_e32 v19, 0xffff0000, v66
	v_pk_add_f32 v[6:7], v[6:7], v[14:15]
	v_pk_add_f32 v[4:5], v[4:5], v[12:13]
	v_cvt_pk_bf16_f32 v10, v20, v21
	v_lshlrev_b32_e32 v20, 16, v67
	v_and_b32_e32 v21, 0xffff0000, v67
	v_pk_add_f32 v[14:15], v[0:1], v[18:19]
	v_mul_f32_e32 v0, v5, v5
	v_mul_f32_e32 v1, v7, v7
	v_pk_add_f32 v[12:13], v[2:3], v[20:21]
	v_fmac_f32_e32 v0, v4, v4
	v_fmac_f32_e32 v1, v6, v6
	v_add_f32_e32 v0, v0, v1
	v_mul_f32_e32 v1, v15, v15
	v_mul_f32_e32 v2, v13, v13
	v_fmac_f32_e32 v1, v14, v14
	v_fmac_f32_e32 v2, v12, v12
	v_add_f32_e32 v1, v1, v2
	v_add_f32_e32 v0, v0, v1
	v_add_f32_e32 v3, v22, v0
	v_mov_b32_e32 v18, v3
	s_nop 1
	v_permlane16_swap_b32_e32 v3, v18
	v_add_u32_e32 v16, 0xb0, v166
	s_waitcnt lgkmcnt(1)
	v_ashrrev_i32_e32 v17, 31, v16
	v_lshlrev_b64 v[16:17], 12, v[16:17]
	v_lshl_add_u64 v[0:1], s[28:29], 0, v[16:17]
	v_lshl_add_u64 v[16:17], v[164:165], 1, v[0:1]
	s_waitcnt lgkmcnt(0)
	v_add_f32_e32 v0, v3, v18
	v_mov_b32_e32 v1, v0
	s_nop 1
	v_permlane32_swap_b32_e32 v0, v1
	v_cvt_pk_bf16_f32 v2, v4, v5
	v_cvt_pk_bf16_f32 v3, v6, v7
	v_cvt_pk_bf16_f32 v4, v14, v15
	v_cvt_pk_bf16_f32 v5, v12, v13
	global_store_dwordx4 v[16:17], v[8:11], off
	global_store_dwordx4 v[16:17], v[2:5], off offset:256
	s_and_saveexec_b64 s[48:49], s[6:7]
	s_cbranch_execz .LBB0_726
	s_waitcnt lgkmcnt(0)
	v_add_f32_e32 v0, v0, v1
	ds_write_b32 v183, v0 offset:2816

.LBB0_978:
	v_lshrrev_b32_e32 v128, 1, v182
	v_and_b32_e32 v128, 56, v128
	s_lshl_b32 s24, s61, 8
	v_add_u32_e32 v185, s43, v128
	v_add_u32_e32 v172, s24, v183
	v_lshlrev_b32_e32 v160, 1, v185
	v_ashrrev_i32_e32 v173, 31, v172
	v_lshl_add_u64 v[176:177], s[28:29], 0, v[160:161]
	v_lshlrev_b64 v[128:129], 12, v[172:173]
	v_lshl_add_u64 v[128:129], v[176:177], 0, v[128:129]
	global_load_dwordx4 v[166:169], v[128:129], off
	global_load_dwordx4 v[186:189], v[128:129], off offset:256
	v_or_b32_e32 v128, 16, v172
	v_or_b32_e32 v130, 32, v172
	v_or_b32_e32 v132, 48, v172
	v_ashrrev_i32_e32 v129, 31, v128
	v_ashrrev_i32_e32 v131, 31, v130
	v_ashrrev_i32_e32 v133, 31, v132
	v_lshlrev_b64 v[128:129], 12, v[128:129]
	v_lshlrev_b64 v[130:131], 12, v[130:131]
	v_lshlrev_b64 v[132:133], 12, v[132:133]
	v_lshl_add_u64 v[128:129], v[176:177], 0, v[128:129]
	v_lshl_add_u64 v[130:131], v[176:177], 0, v[130:131]
	v_lshl_add_u64 v[170:171], v[176:177], 0, v[132:133]
	global_load_dwordx4 v[148:151], v[128:129], off
	global_load_dwordx4 v[144:147], v[128:129], off offset:256
	global_load_dwordx4 v[140:143], v[130:131], off
	global_load_dwordx4 v[136:139], v[130:131], off offset:256
	global_load_dwordx4 v[132:135], v[170:171], off
	s_nop 0
	global_load_dwordx4 v[128:131], v[170:171], off offset:256
	v_and_b32_e32 v170, 64, v182
	v_add_u32_e32 v194, 64, v170
	v_xor_b32_e32 v160, 16, v182
	v_cmp_lt_i32_e32 vcc, v160, v194
	s_waitcnt vmcnt(0)
	v_lshlrev_b32_e32 v170, 16, v166
	v_and_b32_e32 v171, 0xffff0000, v166
	v_lshlrev_b32_e32 v166, 16, v167
	v_and_b32_e32 v167, 0xffff0000, v167
	v_lshlrev_b32_e32 v174, 16, v168
	v_and_b32_e32 v175, 0xffff0000, v168
	v_lshlrev_b32_e32 v168, 16, v169
	v_and_b32_e32 v169, 0xffff0000, v169
	v_lshlrev_b32_e32 v190, 16, v186
	v_and_b32_e32 v191, 0xffff0000, v186
	v_lshlrev_b32_e32 v186, 16, v187
	v_and_b32_e32 v187, 0xffff0000, v187
	v_lshlrev_b32_e32 v192, 16, v188
	v_and_b32_e32 v193, 0xffff0000, v188
	v_lshlrev_b32_e32 v188, 16, v189
	v_and_b32_e32 v189, 0xffff0000, v189
	v_pk_add_f32 v[126:127], v[126:127], v[166:167]
	v_pk_add_f32 v[124:125], v[124:125], v[170:171]
	v_pk_add_f32 v[122:123], v[122:123], v[168:169]
	v_pk_add_f32 v[120:121], v[120:121], v[174:175]
	v_pk_add_f32 v[118:119], v[118:119], v[186:187]
	v_pk_add_f32 v[116:117], v[116:117], v[190:191]
	v_pk_add_f32 v[114:115], v[114:115], v[188:189]
	v_pk_add_f32 v[112:113], v[112:113], v[192:193]
	v_mul_f32_e32 v166, v125, v125
	v_mul_f32_e32 v167, v127, v127
	v_mul_f32_e32 v168, v121, v121
	v_mul_f32_e32 v169, v123, v123
	v_mul_f32_e32 v170, v117, v117
	v_mul_f32_e32 v171, v119, v119
	v_mul_f32_e32 v174, v113, v113
	v_mul_f32_e32 v175, v115, v115
	v_fmac_f32_e32 v166, v124, v124
	v_fmac_f32_e32 v167, v126, v126
	v_fmac_f32_e32 v168, v120, v120
	v_fmac_f32_e32 v169, v122, v122
	v_fmac_f32_e32 v170, v116, v116
	v_fmac_f32_e32 v171, v118, v118
	v_fmac_f32_e32 v174, v112, v112
	v_fmac_f32_e32 v175, v114, v114
	v_add_f32_e32 v166, v166, v167
	v_add_f32_e32 v167, v168, v169
	v_add_f32_e32 v168, v170, v171
	v_add_f32_e32 v169, v174, v175
	v_cndmask_b32_e32 v160, v182, v160, vcc
	v_add_f32_e32 v166, v166, v167
	v_add_f32_e32 v167, v168, v169
	v_lshlrev_b32_e32 v160, 2, v160
	v_add_f32_e32 v166, v166, v167
	v_mov_b32_e32 v167, v166
	s_nop 1
	v_permlane16_swap_b32_e32 v166, v167
	v_xor_b32_e32 v168, 32, v182
	v_cmp_lt_i32_e32 vcc, v168, v194
	s_waitcnt lgkmcnt(0)
	v_add_f32_e32 v166, v166, v167
	v_cndmask_b32_e32 v168, v182, v168, vcc
	v_lshlrev_b32_e32 v186, 2, v168
	v_mov_b32_e32 v167, v166
	s_nop 1
	v_permlane32_swap_b32_e32 v166, v167
	v_cmp_gt_u32_e32 vcc, 16, v182
	s_and_saveexec_b64 s[20:21], vcc
	s_cbranch_execz .LBB0_980
	s_waitcnt lgkmcnt(0)
	v_add_f32_e32 v166, v166, v167
	v_lshl_add_u32 v167, v182, 4, s44
	ds_write_b32 v167, v166
.LBB0_980:
	s_or_b64 exec, exec, s[20:21]
	v_lshlrev_b32_e32 v166, 16, v148
	s_waitcnt lgkmcnt(0)
	v_and_b32_e32 v167, 0xffff0000, v148
	v_lshlrev_b32_e32 v148, 16, v149
	v_and_b32_e32 v149, 0xffff0000, v149
	v_pk_add_f32 v[110:111], v[110:111], v[148:149]
	v_pk_add_f32 v[108:109], v[108:109], v[166:167]
	v_lshlrev_b32_e32 v168, 16, v150
	v_and_b32_e32 v169, 0xffff0000, v150
	v_lshlrev_b32_e32 v150, 16, v151
	v_and_b32_e32 v151, 0xffff0000, v151
	v_mul_f32_e32 v148, v109, v109
	v_mul_f32_e32 v149, v111, v111
	v_pk_add_f32 v[106:107], v[106:107], v[150:151]
	v_pk_add_f32 v[104:105], v[104:105], v[168:169]
	v_fmac_f32_e32 v148, v108, v108
	v_fmac_f32_e32 v149, v110, v110
	v_add_f32_e32 v148, v148, v149
	v_mul_f32_e32 v149, v105, v105
	v_mul_f32_e32 v150, v107, v107
	v_fmac_f32_e32 v149, v104, v104
	v_fmac_f32_e32 v150, v106, v106
	v_add_f32_e32 v149, v149, v150
	v_add_f32_e32 v166, v148, v149
	v_lshlrev_b32_e32 v148, 16, v144
	v_and_b32_e32 v149, 0xffff0000, v144
	v_lshlrev_b32_e32 v144, 16, v145
	v_and_b32_e32 v145, 0xffff0000, v145
	v_pk_add_f32 v[102:103], v[102:103], v[144:145]
	v_pk_add_f32 v[100:101], v[100:101], v[148:149]
	v_lshlrev_b32_e32 v150, 16, v146
	v_and_b32_e32 v151, 0xffff0000, v146
	v_lshlrev_b32_e32 v146, 16, v147
	v_and_b32_e32 v147, 0xffff0000, v147
	v_mul_f32_e32 v144, v101, v101
	v_mul_f32_e32 v145, v103, v103
	v_pk_add_f32 v[98:99], v[98:99], v[146:147]
	v_pk_add_f32 v[96:97], v[96:97], v[150:151]
	v_fmac_f32_e32 v144, v100, v100
	v_fmac_f32_e32 v145, v102, v102
	v_add_f32_e32 v144, v144, v145
	v_mul_f32_e32 v145, v97, v97
	v_mul_f32_e32 v146, v99, v99
	v_fmac_f32_e32 v145, v96, v96
	v_fmac_f32_e32 v146, v98, v98
	v_add_f32_e32 v145, v145, v146
	v_add_f32_e32 v144, v144, v145
	v_add_f32_e32 v144, v166, v144
	v_mov_b32_e32 v145, v144
	s_nop 1
	v_permlane16_swap_b32_e32 v144, v145
	s_waitcnt lgkmcnt(0)
	v_add_f32_e32 v144, v144, v145
	v_mov_b32_e32 v145, v144
	s_nop 1
	v_permlane32_swap_b32_e32 v144, v145
	s_and_saveexec_b64 s[20:21], vcc
	s_cbranch_execz .LBB0_982
	s_waitcnt lgkmcnt(0)
	v_add_f32_e32 v144, v144, v145
	v_lshl_add_u32 v145, v182, 4, s45
	ds_write_b32 v145, v144
.LBB0_982:
	s_or_b64 exec, exec, s[20:21]
	v_lshlrev_b32_e32 v144, 16, v140
	s_waitcnt lgkmcnt(0)
	v_and_b32_e32 v145, 0xffff0000, v140
	v_lshlrev_b32_e32 v140, 16, v141
	v_and_b32_e32 v141, 0xffff0000, v141
	v_lshlrev_b32_e32 v146, 16, v142
	v_and_b32_e32 v147, 0xffff0000, v142
	v_pk_add_f32 v[94:95], v[94:95], v[140:141]
	v_pk_add_f32 v[92:93], v[92:93], v[144:145]
	v_lshlrev_b32_e32 v142, 16, v143
	v_and_b32_e32 v143, 0xffff0000, v143
	v_pk_add_f32 v[140:141], v[88:89], v[146:147]
	v_mul_f32_e32 v88, v93, v93
	v_mul_f32_e32 v89, v95, v95
	v_pk_add_f32 v[90:91], v[90:91], v[142:143]
	v_fmac_f32_e32 v88, v92, v92
	v_fmac_f32_e32 v89, v94, v94
	v_add_f32_e32 v88, v88, v89
	v_mul_f32_e32 v89, v141, v141
	v_mul_f32_e32 v142, v91, v91
	v_fmac_f32_e32 v89, v140, v140
	v_fmac_f32_e32 v142, v90, v90
	v_add_f32_e32 v89, v89, v142
	v_add_f32_e32 v146, v88, v89
	v_lshlrev_b32_e32 v142, 16, v136
	v_and_b32_e32 v143, 0xffff0000, v136
	v_lshlrev_b32_e32 v88, 16, v137
	v_and_b32_e32 v89, 0xffff0000, v137
	v_lshlrev_b32_e32 v144, 16, v138
	v_and_b32_e32 v145, 0xffff0000, v138
	v_lshlrev_b32_e32 v136, 16, v139
	v_and_b32_e32 v137, 0xffff0000, v139
	v_pk_add_f32 v[88:89], v[86:87], v[88:89]
	v_pk_add_f32 v[138:139], v[84:85], v[142:143]
	v_pk_add_f32 v[142:143], v[80:81], v[144:145]
	v_mul_f32_e32 v80, v139, v139
	v_mul_f32_e32 v81, v89, v89
	v_pk_add_f32 v[136:137], v[82:83], v[136:137]
	v_fmac_f32_e32 v80, v138, v138
	v_fmac_f32_e32 v81, v88, v88
	v_add_f32_e32 v80, v80, v81
	v_mul_f32_e32 v81, v143, v143
	v_mul_f32_e32 v82, v137, v137
	v_fmac_f32_e32 v81, v142, v142
	v_fmac_f32_e32 v82, v136, v136
	v_add_f32_e32 v81, v81, v82
	v_add_f32_e32 v80, v80, v81
	v_add_f32_e32 v80, v146, v80
	v_mov_b32_e32 v81, v80
	s_nop 1
	v_permlane16_swap_b32_e32 v80, v81
	s_waitcnt lgkmcnt(0)
	v_add_f32_e32 v80, v80, v81
	v_mov_b32_e32 v81, v80
	s_nop 1
	v_permlane32_swap_b32_e32 v80, v81
	s_and_saveexec_b64 s[20:21], vcc
	s_cbranch_execz .LBB0_984
	s_waitcnt lgkmcnt(0)
	v_add_f32_e32 v80, v80, v81
	v_lshl_add_u32 v81, v182, 4, s46
	ds_write_b32 v81, v80
.LBB0_984:
	s_or_b64 exec, exec, s[20:21]
	v_lshlrev_b32_e32 v80, 16, v132
	s_waitcnt lgkmcnt(0)
	v_and_b32_e32 v81, 0xffff0000, v132
	v_lshlrev_b32_e32 v82, 16, v133
	v_and_b32_e32 v83, 0xffff0000, v133
	v_lshlrev_b32_e32 v84, 16, v134
	v_and_b32_e32 v85, 0xffff0000, v134
	v_pk_add_f32 v[132:133], v[78:79], v[82:83]
	v_pk_add_f32 v[144:145], v[76:77], v[80:81]
	v_lshlrev_b32_e32 v86, 16, v135
	v_and_b32_e32 v87, 0xffff0000, v135
	v_pk_add_f32 v[146:147], v[72:73], v[84:85]
	v_mul_f32_e32 v72, v145, v145
	v_mul_f32_e32 v73, v133, v133
	v_pk_add_f32 v[134:135], v[74:75], v[86:87]
	v_fmac_f32_e32 v72, v144, v144
	v_fmac_f32_e32 v73, v132, v132
	v_add_f32_e32 v72, v72, v73
	v_mul_f32_e32 v73, v147, v147
	v_mul_f32_e32 v74, v135, v135
	v_fmac_f32_e32 v73, v146, v146
	v_fmac_f32_e32 v74, v134, v134
	v_add_f32_e32 v73, v73, v74
	v_add_f32_e32 v80, v72, v73
	v_lshlrev_b32_e32 v72, 16, v128
	v_and_b32_e32 v73, 0xffff0000, v128
	v_lshlrev_b32_e32 v74, 16, v129
	v_and_b32_e32 v75, 0xffff0000, v129
	v_lshlrev_b32_e32 v76, 16, v130
	v_and_b32_e32 v77, 0xffff0000, v130
	v_lshlrev_b32_e32 v78, 16, v131
	v_and_b32_e32 v79, 0xffff0000, v131
	v_pk_add_f32 v[130:131], v[70:71], v[74:75]
	v_pk_add_f32 v[166:167], v[68:69], v[72:73]
	v_pk_add_f32 v[168:169], v[64:65], v[76:77]
	v_mul_f32_e32 v64, v167, v167
	v_mul_f32_e32 v65, v131, v131
	v_pk_add_f32 v[150:151], v[66:67], v[78:79]
	v_fmac_f32_e32 v64, v166, v166
	v_fmac_f32_e32 v65, v130, v130
	v_add_f32_e32 v64, v64, v65
	v_mul_f32_e32 v65, v169, v169
	v_mul_f32_e32 v66, v151, v151
	v_fmac_f32_e32 v65, v168, v168
	v_fmac_f32_e32 v66, v150, v150
	v_add_f32_e32 v65, v65, v66
	v_add_f32_e32 v64, v64, v65
	v_add_f32_e32 v64, v80, v64
	v_mov_b32_e32 v65, v64
	s_nop 1
	v_permlane16_swap_b32_e32 v64, v65
	s_waitcnt lgkmcnt(0)
	v_add_f32_e32 v64, v64, v65
	v_mov_b32_e32 v65, v64
	s_nop 1
	v_permlane32_swap_b32_e32 v64, v65
	s_and_saveexec_b64 s[20:21], vcc
	s_cbranch_execz .LBB0_986
	s_waitcnt lgkmcnt(0)
	v_add_f32_e32 v64, v64, v65
	v_lshl_add_u32 v65, v182, 4, s47
	ds_write_b32 v65, v64
.LBB0_986:
	s_or_b64 exec, exec, s[20:21]
	v_add_u32_e32 v174, 0x80, v172
	v_ashrrev_i32_e32 v175, 31, v174
	s_waitcnt lgkmcnt(0)
	v_lshlrev_b64 v[64:65], 12, v[174:175]
	v_lshl_add_u64 v[64:65], v[176:177], 0, v[64:65]
	global_load_dwordx4 v[188:191], v[64:65], off
	global_load_dwordx4 v[192:195], v[64:65], off offset:256
	v_add_u32_e32 v170, 0x90, v172
	v_add_u32_e32 v148, 0xa0, v172
	v_add_u32_e32 v128, 0xb0, v172
	v_ashrrev_i32_e32 v171, 31, v170
	v_ashrrev_i32_e32 v149, 31, v148
	v_ashrrev_i32_e32 v129, 31, v128
	v_lshlrev_b64 v[64:65], 12, v[170:171]
	v_lshlrev_b64 v[66:67], 12, v[148:149]
	v_lshlrev_b64 v[68:69], 12, v[128:129]
	v_lshl_add_u64 v[64:65], v[176:177], 0, v[64:65]
	v_lshl_add_u64 v[66:67], v[176:177], 0, v[66:67]
	v_lshl_add_u64 v[176:177], v[176:177], 0, v[68:69]
	global_load_dwordx4 v[84:87], v[64:65], off
	global_load_dwordx4 v[80:83], v[64:65], off offset:256
	global_load_dwordx4 v[76:79], v[66:67], off
	global_load_dwordx4 v[72:75], v[66:67], off offset:256
	global_load_dwordx4 v[68:71], v[176:177], off
	s_nop 0
	global_load_dwordx4 v[64:67], v[176:177], off offset:256
	s_waitcnt vmcnt(7)
	v_lshlrev_b32_e32 v176, 16, v188
	v_and_b32_e32 v177, 0xffff0000, v188
	v_lshlrev_b32_e32 v188, 16, v189
	v_and_b32_e32 v189, 0xffff0000, v189
	v_lshlrev_b32_e32 v196, 16, v190
	v_and_b32_e32 v197, 0xffff0000, v190
	v_lshlrev_b32_e32 v190, 16, v191
	v_and_b32_e32 v191, 0xffff0000, v191
	s_waitcnt vmcnt(6)
	v_lshlrev_b32_e32 v198, 16, v192
	v_and_b32_e32 v199, 0xffff0000, v192
	v_lshlrev_b32_e32 v192, 16, v193
	v_and_b32_e32 v193, 0xffff0000, v193
	v_lshlrev_b32_e32 v200, 16, v194
	v_and_b32_e32 v201, 0xffff0000, v194
	v_lshlrev_b32_e32 v194, 16, v195
	v_and_b32_e32 v195, 0xffff0000, v195
	v_pk_add_f32 v[62:63], v[62:63], v[188:189]
	v_pk_add_f32 v[60:61], v[60:61], v[176:177]
	v_pk_add_f32 v[58:59], v[58:59], v[190:191]
	v_pk_add_f32 v[56:57], v[56:57], v[196:197]
	v_pk_add_f32 v[54:55], v[54:55], v[192:193]
	v_pk_add_f32 v[52:53], v[52:53], v[198:199]
	v_pk_add_f32 v[50:51], v[50:51], v[194:195]
	v_pk_add_f32 v[48:49], v[48:49], v[200:201]
	v_mul_f32_e32 v176, v61, v61
	v_mul_f32_e32 v177, v63, v63
	v_mul_f32_e32 v187, v57, v57
	v_mul_f32_e32 v188, v59, v59
	v_mul_f32_e32 v189, v53, v53
	v_mul_f32_e32 v190, v55, v55
	v_mul_f32_e32 v191, v49, v49
	v_mul_f32_e32 v192, v51, v51
	v_fmac_f32_e32 v176, v60, v60
	v_fmac_f32_e32 v177, v62, v62
	v_fmac_f32_e32 v187, v56, v56
	v_fmac_f32_e32 v188, v58, v58
	v_fmac_f32_e32 v189, v52, v52
	v_fmac_f32_e32 v190, v54, v54
	v_fmac_f32_e32 v191, v48, v48
	v_fmac_f32_e32 v192, v50, v50
	v_add_f32_e32 v176, v176, v177
	v_add_f32_e32 v177, v187, v188
	v_add_f32_e32 v187, v189, v190
	v_add_f32_e32 v188, v191, v192
	v_add_f32_e32 v176, v176, v177
	v_add_f32_e32 v177, v187, v188
	v_add_f32_e32 v176, v176, v177
	v_mov_b32_e32 v177, v176
	s_nop 1
	v_permlane16_swap_b32_e32 v176, v177
	s_waitcnt lgkmcnt(0)
	v_add_f32_e32 v176, v176, v177
	v_mov_b32_e32 v177, v176
	s_nop 1
	v_permlane32_swap_b32_e32 v176, v177
	s_and_saveexec_b64 s[20:21], vcc
	s_cbranch_execz .LBB0_988
	v_lshl_add_u32 v187, v182, 4, s48
	s_waitcnt lgkmcnt(0)
	v_add_f32_e32 v176, v176, v177
	ds_write_b32 v187, v176
.LBB0_988:
	s_or_b64 exec, exec, s[20:21]
	s_waitcnt vmcnt(5)
	v_lshlrev_b32_e32 v176, 16, v84
	s_waitcnt lgkmcnt(0)
	v_and_b32_e32 v177, 0xffff0000, v84
	v_lshlrev_b32_e32 v84, 16, v85
	v_and_b32_e32 v85, 0xffff0000, v85
	v_pk_add_f32 v[46:47], v[46:47], v[84:85]
	v_pk_add_f32 v[44:45], v[44:45], v[176:177]
	v_lshlrev_b32_e32 v188, 16, v86
	v_and_b32_e32 v189, 0xffff0000, v86
	v_lshlrev_b32_e32 v86, 16, v87
	v_and_b32_e32 v87, 0xffff0000, v87
	v_mul_f32_e32 v84, v45, v45
	v_mul_f32_e32 v85, v47, v47
	v_pk_add_f32 v[42:43], v[42:43], v[86:87]
	v_pk_add_f32 v[40:41], v[40:41], v[188:189]
	v_fmac_f32_e32 v84, v44, v44
	v_fmac_f32_e32 v85, v46, v46
	v_add_f32_e32 v84, v84, v85
	v_mul_f32_e32 v85, v41, v41
	v_mul_f32_e32 v86, v43, v43
	v_fmac_f32_e32 v85, v40, v40
	v_fmac_f32_e32 v86, v42, v42
	v_add_f32_e32 v85, v85, v86
	v_add_f32_e32 v176, v84, v85
	s_waitcnt vmcnt(4)
	v_lshlrev_b32_e32 v84, 16, v80
	v_and_b32_e32 v85, 0xffff0000, v80
	v_lshlrev_b32_e32 v80, 16, v81
	v_and_b32_e32 v81, 0xffff0000, v81
	v_pk_add_f32 v[38:39], v[38:39], v[80:81]
	v_pk_add_f32 v[36:37], v[36:37], v[84:85]
	v_lshlrev_b32_e32 v86, 16, v82
	v_and_b32_e32 v87, 0xffff0000, v82
	v_lshlrev_b32_e32 v82, 16, v83
	v_and_b32_e32 v83, 0xffff0000, v83
	v_mul_f32_e32 v80, v37, v37
	v_mul_f32_e32 v81, v39, v39
	v_pk_add_f32 v[34:35], v[34:35], v[82:83]
	v_pk_add_f32 v[32:33], v[32:33], v[86:87]
	v_fmac_f32_e32 v80, v36, v36
	v_fmac_f32_e32 v81, v38, v38
	v_add_f32_e32 v80, v80, v81
	v_mul_f32_e32 v81, v33, v33
	v_mul_f32_e32 v82, v35, v35
	v_fmac_f32_e32 v81, v32, v32
	v_fmac_f32_e32 v82, v34, v34
	v_add_f32_e32 v81, v81, v82
	v_add_f32_e32 v80, v80, v81
	v_add_f32_e32 v80, v176, v80
	v_mov_b32_e32 v81, v80
	s_nop 1
	v_permlane16_swap_b32_e32 v80, v81
	s_waitcnt lgkmcnt(0)
	v_add_f32_e32 v80, v80, v81
	v_mov_b32_e32 v81, v80
	s_nop 1
	v_permlane32_swap_b32_e32 v80, v81
	s_and_saveexec_b64 s[20:21], vcc
	s_cbranch_execz .LBB0_990
	v_lshl_add_u32 v82, v182, 4, s49
	s_waitcnt lgkmcnt(0)
	v_add_f32_e32 v80, v80, v81
	ds_write_b32 v82, v80
.LBB0_990:
	s_or_b64 exec, exec, s[20:21]
	s_waitcnt vmcnt(3)
	v_lshlrev_b32_e32 v80, 16, v76
	s_waitcnt lgkmcnt(0)
	v_and_b32_e32 v81, 0xffff0000, v76
	v_lshlrev_b32_e32 v76, 16, v77
	v_and_b32_e32 v77, 0xffff0000, v77
	v_pk_add_f32 v[30:31], v[30:31], v[76:77]
	v_pk_add_f32 v[28:29], v[28:29], v[80:81]
	v_lshlrev_b32_e32 v82, 16, v78
	v_and_b32_e32 v83, 0xffff0000, v78
	v_lshlrev_b32_e32 v78, 16, v79
	v_and_b32_e32 v79, 0xffff0000, v79
	v_mul_f32_e32 v76, v29, v29
	v_mul_f32_e32 v77, v31, v31
	v_pk_add_f32 v[26:27], v[26:27], v[78:79]
	v_pk_add_f32 v[24:25], v[24:25], v[82:83]
	v_fmac_f32_e32 v76, v28, v28
	v_fmac_f32_e32 v77, v30, v30
	v_add_f32_e32 v76, v76, v77
	v_mul_f32_e32 v77, v25, v25
	v_mul_f32_e32 v78, v27, v27
	v_fmac_f32_e32 v77, v24, v24
	v_fmac_f32_e32 v78, v26, v26
	v_add_f32_e32 v77, v77, v78
	v_add_f32_e32 v80, v76, v77
	s_waitcnt vmcnt(2)
	v_lshlrev_b32_e32 v76, 16, v72
	v_and_b32_e32 v77, 0xffff0000, v72
	v_lshlrev_b32_e32 v72, 16, v73
	v_and_b32_e32 v73, 0xffff0000, v73
	v_pk_add_f32 v[22:23], v[22:23], v[72:73]
	v_pk_add_f32 v[20:21], v[20:21], v[76:77]
	v_lshlrev_b32_e32 v78, 16, v74
	v_and_b32_e32 v79, 0xffff0000, v74
	v_lshlrev_b32_e32 v74, 16, v75
	v_and_b32_e32 v75, 0xffff0000, v75
	v_mul_f32_e32 v72, v21, v21
	v_mul_f32_e32 v73, v23, v23
	v_pk_add_f32 v[18:19], v[18:19], v[74:75]
	v_pk_add_f32 v[16:17], v[16:17], v[78:79]
	v_fmac_f32_e32 v72, v20, v20
	v_fmac_f32_e32 v73, v22, v22
	v_add_f32_e32 v72, v72, v73
	v_mul_f32_e32 v73, v17, v17
	v_mul_f32_e32 v74, v19, v19
	v_fmac_f32_e32 v73, v16, v16
	v_fmac_f32_e32 v74, v18, v18
	v_add_f32_e32 v73, v73, v74
	v_add_f32_e32 v72, v72, v73
	v_add_f32_e32 v72, v80, v72
	v_mov_b32_e32 v73, v72
	s_nop 1
	v_permlane16_swap_b32_e32 v72, v73
	s_waitcnt lgkmcnt(0)
	v_add_f32_e32 v72, v72, v73
	v_mov_b32_e32 v73, v72
	s_nop 1
	v_permlane32_swap_b32_e32 v72, v73
	s_and_saveexec_b64 s[20:21], vcc
	s_cbranch_execz .LBB0_992
	v_lshl_add_u32 v74, v182, 4, s50
	s_waitcnt lgkmcnt(0)
	v_add_f32_e32 v72, v72, v73
	ds_write_b32 v74, v72
.LBB0_992:
	s_or_b64 exec, exec, s[20:21]
	s_waitcnt vmcnt(1)
	v_lshlrev_b32_e32 v74, 16, v68
	v_and_b32_e32 v75, 0xffff0000, v68
	v_lshlrev_b32_e32 v68, 16, v69
	v_and_b32_e32 v69, 0xffff0000, v69
	v_lshlrev_b32_e32 v76, 16, v70
	v_and_b32_e32 v77, 0xffff0000, v70
	v_lshlrev_b32_e32 v70, 16, v71
	v_and_b32_e32 v71, 0xffff0000, v71
	s_waitcnt lgkmcnt(0)
	v_pk_add_f32 v[72:73], v[14:15], v[68:69]
	v_pk_add_f32 v[74:75], v[12:13], v[74:75]
	v_pk_add_f32 v[68:69], v[10:11], v[70:71]
	v_pk_add_f32 v[70:71], v[8:9], v[76:77]
	v_mul_f32_e32 v8, v75, v75
	v_mul_f32_e32 v9, v73, v73
	v_fmac_f32_e32 v8, v74, v74
	v_fmac_f32_e32 v9, v72, v72
	v_add_f32_e32 v8, v8, v9
	v_mul_f32_e32 v9, v71, v71
	v_mul_f32_e32 v10, v69, v69
	v_fmac_f32_e32 v9, v70, v70
	v_fmac_f32_e32 v10, v68, v68
	v_add_f32_e32 v9, v9, v10
	v_add_f32_e32 v80, v8, v9
	s_waitcnt vmcnt(0)
	v_lshlrev_b32_e32 v8, 16, v64
	v_and_b32_e32 v9, 0xffff0000, v64
	v_lshlrev_b32_e32 v10, 16, v65
	v_and_b32_e32 v11, 0xffff0000, v65
	v_lshlrev_b32_e32 v12, 16, v66
	v_and_b32_e32 v13, 0xffff0000, v66
	v_pk_add_f32 v[76:77], v[6:7], v[10:11]
	v_pk_add_f32 v[78:79], v[4:5], v[8:9]
	v_lshlrev_b32_e32 v14, 16, v67
	v_and_b32_e32 v15, 0xffff0000, v67
	v_pk_add_f32 v[66:67], v[0:1], v[12:13]
	v_mul_f32_e32 v0, v79, v79
	v_mul_f32_e32 v1, v77, v77
	v_pk_add_f32 v[64:65], v[2:3], v[14:15]
	v_fmac_f32_e32 v0, v78, v78
	v_fmac_f32_e32 v1, v76, v76
	v_add_f32_e32 v0, v0, v1
	v_mul_f32_e32 v1, v67, v67
	v_mul_f32_e32 v2, v65, v65
	v_fmac_f32_e32 v1, v66, v66
	v_fmac_f32_e32 v2, v64, v64
	v_add_f32_e32 v1, v1, v2
	v_add_f32_e32 v0, v0, v1
	v_add_f32_e32 v0, v80, v0
	v_mov_b32_e32 v1, v0
	s_nop 1
	v_permlane16_swap_b32_e32 v0, v1
	s_waitcnt lgkmcnt(0)
	v_add_f32_e32 v0, v0, v1
	v_mov_b32_e32 v1, v0
	s_nop 1
	v_permlane32_swap_b32_e32 v0, v1
	s_and_saveexec_b64 s[20:21], vcc
	s_cbranch_execz .LBB0_994
	v_lshl_add_u32 v2, v182, 4, s51
	s_waitcnt lgkmcnt(0)
	v_add_f32_e32 v0, v0, v1
	ds_write_b32 v2, v0
